# E1E5 waits + LRU prio + LRU MFMA ds_read prefetch + nt hints on P1 x loads, Gin proj stores, P5 y stores
# speedup vs baseline: 1.0251x; 1.0251x over previous
.LBB0_52:
	s_add_u32 s22, s4, s21
	s_addc_u32 s23, s5, 0
	s_lshl_b64 s[30:31], s[22:23], 12
	v_lshl_add_u64 v[32:33], v[106:107], 0, s[30:31]
	global_load_dwordx4 v[92:95], v[32:33], off nt
	global_load_dwordx4 v[88:91], v[32:33], off offset:1024 nt
	global_load_dwordx4 v[80:83], v[32:33], off offset:3072 nt
	global_load_dwordx4 v[84:87], v[32:33], off offset:2048 nt
	v_add_co_u32_e32 v34, vcc, 0x1000, v32
	s_lshl_b64 s[30:31], s[22:23], 11
	s_nop 0
	v_addc_co_u32_e32 v35, vcc, 0, v33, vcc
	global_load_dwordx4 v[76:79], v[34:35], off nt
	global_load_dwordx4 v[72:75], v[34:35], off offset:1024 nt
	global_load_dwordx4 v[64:67], v[34:35], off offset:3072 nt
	global_load_dwordx4 v[68:71], v[34:35], off offset:2048 nt
	v_add_co_u32_e32 v34, vcc, 0x2000, v32
	s_mov_b32 s29, 0
	s_nop 0
	v_addc_co_u32_e32 v35, vcc, 0, v33, vcc
	global_load_dwordx4 v[60:63], v[34:35], off nt
	global_load_dwordx4 v[56:59], v[34:35], off offset:1024 nt
	global_load_dwordx4 v[48:51], v[34:35], off offset:3072 nt
	global_load_dwordx4 v[52:55], v[34:35], off offset:2048 nt
	v_add_co_u32_e32 v32, vcc, s26, v32
	s_waitcnt vmcnt(11)
	v_pk_mul_f32 v[134:135], v[94:95], v[94:95]
	v_addc_co_u32_e32 v33, vcc, 0, v33, vcc
	global_load_dwordx4 v[44:47], v[32:33], off nt
	global_load_dwordx4 v[40:43], v[32:33], off offset:1024 nt
	global_load_dwordx4 v[36:39], v[32:33], off offset:2048 nt
	s_nop 0
	global_load_dwordx4 v[32:35], v[32:33], off offset:3072 nt
	v_pk_mul_f32 v[136:137], v[92:93], v[92:93]
	s_waitcnt vmcnt(14)
	v_pk_mul_f32 v[138:139], v[90:91], v[90:91]
	v_pk_mul_f32 v[140:141], v[88:89], v[88:89]
	s_waitcnt vmcnt(13)
	v_mul_f32_e32 v145, v82, v82
	s_waitcnt vmcnt(12)
	v_mul_f32_e32 v142, v85, v85
	v_mul_f32_e32 v144, v87, v87
	v_mul_f32_e32 v148, v83, v83
	v_pk_mov_b32 v[146:147], v[136:137], v[134:135] op_sel:[1,0]
	v_mov_b32_e32 v137, v135
	v_pk_mov_b32 v[134:135], v[140:141], v[138:139] op_sel:[1,0]
	v_mov_b32_e32 v141, v139
	v_pk_fma_f32 v[138:139], v[84:85], v[84:85], v[142:143] op_sel_hi:[1,1,0]
	v_pk_fma_f32 v[142:143], v[86:87], v[86:87], v[144:145] op_sel_hi:[1,1,0]
	v_pk_add_f32 v[136:137], v[146:147], v[136:137]
	v_pk_add_f32 v[134:135], v[134:135], v[140:141]
	v_mov_b32_e32 v139, v145
	v_mov_b32_e32 v143, v148
	s_waitcnt vmcnt(11)
	v_pk_mul_f32 v[140:141], v[78:79], v[78:79]
	v_pk_mul_f32 v[144:145], v[76:77], v[76:77]
	s_waitcnt vmcnt(10)
	v_pk_mul_f32 v[146:147], v[74:75], v[74:75]
	v_pk_mul_f32 v[148:149], v[72:73], v[72:73]
	v_pk_add_f32 v[138:139], v[138:139], v[142:143]
	v_pk_mov_b32 v[142:143], v[144:145], v[140:141] op_sel:[1,0]
	v_mov_b32_e32 v145, v141
	v_pk_mov_b32 v[140:141], v[148:149], v[146:147] op_sel:[1,0]
	v_mov_b32_e32 v149, v147
	v_mul_f32_e32 v156, v80, v80
	v_mul_f32_e32 v157, v81, v81
	s_waitcnt vmcnt(8)
	v_mul_f32_e32 v150, v69, v69
	v_mul_f32_e32 v152, v71, v71
	v_pk_add_f32 v[136:137], v[136:137], v[136:137] op_sel:[0,1] op_sel_hi:[1,0]
	v_pk_add_f32 v[134:135], v[134:135], v[134:135] op_sel:[0,1] op_sel_hi:[1,0]
	v_pk_add_f32 v[142:143], v[142:143], v[144:145]
	v_pk_add_f32 v[140:141], v[140:141], v[148:149]
	v_mul_f32_e32 v158, v66, v66
	v_mul_f32_e32 v159, v67, v67
	v_mul_f32_e32 v160, v64, v64
	v_mul_f32_e32 v161, v65, v65
	v_pk_fma_f32 v[150:151], v[68:69], v[68:69], v[150:151] op_sel_hi:[1,1,0]
	v_pk_fma_f32 v[152:153], v[70:71], v[70:71], v[152:153] op_sel_hi:[1,1,0]
	v_mov_b32_e32 v137, v156
	v_mov_b32_e32 v135, v157
	v_pk_add_f32 v[142:143], v[142:143], v[142:143] op_sel:[0,1] op_sel_hi:[1,0]
	v_pk_add_f32 v[140:141], v[140:141], v[140:141] op_sel:[0,1] op_sel_hi:[1,0]
	s_waitcnt vmcnt(7)
	v_pk_mul_f32 v[146:147], v[62:63], v[62:63]
	v_pk_mul_f32 v[154:155], v[60:61], v[60:61]
	v_mov_b32_e32 v151, v158
	v_mov_b32_e32 v153, v159
	v_pk_add_f32 v[134:135], v[136:137], v[134:135]
	v_mov_b32_e32 v143, v160
	v_mov_b32_e32 v141, v161
	v_pk_mov_b32 v[144:145], v[154:155], v[146:147] op_sel:[1,0]
	v_mov_b32_e32 v155, v147
	v_pk_add_f32 v[136:137], v[150:151], v[152:153]
	v_pk_add_f32 v[134:135], v[134:135], v[138:139]
	v_pk_add_f32 v[138:139], v[142:143], v[140:141]
	s_waitcnt vmcnt(6)
	v_pk_mul_f32 v[140:141], v[58:59], v[58:59]
	v_pk_mul_f32 v[142:143], v[56:57], v[56:57]
	v_pk_add_f32 v[136:137], v[138:139], v[136:137]
	v_pk_add_f32 v[138:139], v[144:145], v[154:155]
	v_pk_mov_b32 v[144:145], v[142:143], v[140:141] op_sel:[1,0]
	v_mov_b32_e32 v143, v141
	v_pk_add_f32 v[140:141], v[144:145], v[142:143]
	s_waitcnt vmcnt(5)
	v_mul_f32_e32 v142, v48, v48
	v_mul_f32_e32 v143, v49, v49
	v_pk_add_f32 v[138:139], v[138:139], v[138:139] op_sel:[0,1] op_sel_hi:[1,0]
	v_pk_add_f32 v[140:141], v[140:141], v[140:141] op_sel:[0,1] op_sel_hi:[1,0]
	v_mov_b32_e32 v139, v142
	v_mov_b32_e32 v141, v143
	v_pk_add_f32 v[138:139], v[138:139], v[140:141]
	s_waitcnt vmcnt(4)
	v_mul_f32_e32 v140, v53, v53
	v_mul_f32_e32 v142, v55, v55
	v_mul_f32_e32 v144, v50, v50
	v_mul_f32_e32 v145, v51, v51
	v_pk_fma_f32 v[140:141], v[52:53], v[52:53], v[140:141] op_sel_hi:[1,1,0]
	v_pk_fma_f32 v[142:143], v[54:55], v[54:55], v[142:143] op_sel_hi:[1,1,0]
	v_mov_b32_e32 v141, v144
	v_mov_b32_e32 v143, v145
	v_mov_b32_e32 v144, v136
	v_mov_b32_e32 v145, v134
	v_mov_b32_e32 v134, v137
	v_pk_add_f32 v[134:135], v[144:145], v[134:135]
	ds_bpermute_b32 v137, v125, v135
	ds_bpermute_b32 v136, v125, v134
	v_pk_add_f32 v[140:141], v[140:141], v[142:143]
	s_waitcnt vmcnt(3)
	v_pk_mul_f32 v[142:143], v[44:45], v[44:45]
	v_pk_add_f32 v[138:139], v[138:139], v[140:141]
	v_pk_mul_f32 v[140:141], v[46:47], v[46:47]
	s_waitcnt lgkmcnt(0)
	v_pk_add_f32 v[134:135], v[134:135], v[136:137]
	ds_bpermute_b32 v137, v126, v135
	ds_bpermute_b32 v136, v126, v134
	v_pk_mov_b32 v[144:145], v[142:143], v[140:141] op_sel:[1,0]
	v_mov_b32_e32 v143, v141
	v_pk_add_f32 v[140:141], v[144:145], v[142:143]
	s_waitcnt vmcnt(2)
	v_pk_mul_f32 v[142:143], v[42:43], v[42:43]
	s_waitcnt lgkmcnt(0)
	v_pk_add_f32 v[134:135], v[134:135], v[136:137]
	ds_bpermute_b32 v137, v127, v135
	ds_bpermute_b32 v136, v127, v134
	v_pk_mul_f32 v[144:145], v[40:41], v[40:41]
	v_pk_add_f32 v[140:141], v[140:141], v[140:141] op_sel:[0,1] op_sel_hi:[1,0]
	v_pk_mov_b32 v[146:147], v[144:145], v[142:143] op_sel:[1,0]
	v_mov_b32_e32 v145, v143
	s_waitcnt lgkmcnt(0)
	v_pk_add_f32 v[134:135], v[134:135], v[136:137]
	ds_bpermute_b32 v137, v128, v135
	ds_bpermute_b32 v136, v128, v134
	v_pk_add_f32 v[142:143], v[146:147], v[144:145]
	s_waitcnt vmcnt(0)
	v_mul_f32_e32 v144, v32, v32
	v_mul_f32_e32 v145, v33, v33
	v_pk_add_f32 v[142:143], v[142:143], v[142:143] op_sel:[0,1] op_sel_hi:[1,0]
	s_waitcnt lgkmcnt(0)
	v_pk_add_f32 v[134:135], v[134:135], v[136:137]
	ds_bpermute_b32 v137, v129, v135
	ds_bpermute_b32 v136, v129, v134
	v_mov_b32_e32 v141, v144
	v_mov_b32_e32 v143, v145
	v_pk_add_f32 v[140:141], v[140:141], v[142:143]
	v_mul_f32_e32 v142, v37, v37
	s_waitcnt lgkmcnt(0)
	v_pk_add_f32 v[134:135], v[134:135], v[136:137]
	ds_bpermute_b32 v137, v130, v135
	ds_bpermute_b32 v136, v130, v134
	v_mul_f32_e32 v144, v39, v39
	v_mul_f32_e32 v146, v34, v34
	v_mul_f32_e32 v147, v35, v35
	v_pk_fma_f32 v[142:143], v[36:37], v[36:37], v[142:143] op_sel_hi:[1,1,0]
	v_pk_fma_f32 v[144:145], v[38:39], v[38:39], v[144:145] op_sel_hi:[1,1,0]
	s_waitcnt lgkmcnt(0)
	v_pk_add_f32 v[134:135], v[134:135], v[136:137]
	v_mov_b64_e32 v[136:137], s[18:19]
	v_mov_b32_e32 v143, v146
	v_mov_b32_e32 v145, v147
	v_pk_fma_f32 v[134:135], v[134:135], s[16:17], v[136:137] op_sel_hi:[1,0,0]
	v_pk_add_f32 v[142:143], v[142:143], v[144:145]
	v_mul_f32_e32 v144, 0x4b800000, v135
	v_cmp_gt_f32_e32 vcc, s28, v135
	v_pk_add_f32 v[140:141], v[140:141], v[142:143]
	v_lshl_add_u64 v[142:143], v[100:101], 0, s[30:31]
	v_cndmask_b32_e32 v135, v135, v144, vcc
	v_rsq_f32_e32 v135, v135
	s_nop 0
	v_mul_f32_e32 v144, 0x45800000, v135
	v_cndmask_b32_e32 v144, v135, v144, vcc
	v_pk_mul_f32 v[80:81], v[80:81], v[144:145] op_sel_hi:[1,0]
	v_pk_mul_f32 v[84:85], v[84:85], v[144:145] op_sel_hi:[1,0]
	v_pk_fma_f32 v[80:81], v[118:119], v[80:81], v[28:29]
	v_pk_mul_f32 v[86:87], v[86:87], v[144:145] op_sel_hi:[1,0]
	v_cvt_pk_bf16_f32 v80, v80, v81
	v_mul_f32_e32 v81, 0x4b800000, v134
	v_cmp_gt_f32_e32 vcc, s28, v134
	v_pk_fma_f32 v[86:87], v[108:109], v[86:87], v[18:19]
	v_pk_fma_f32 v[84:85], v[112:113], v[84:85], v[16:17]
	v_pk_mul_f32 v[82:83], v[82:83], v[144:145] op_sel_hi:[1,0]
	v_cndmask_b32_e32 v81, v134, v81, vcc
	v_pk_mul_f32 v[92:93], v[92:93], v[144:145] op_sel_hi:[1,0]
	v_pk_mul_f32 v[94:95], v[94:95], v[144:145] op_sel_hi:[1,0]
	v_cvt_pk_bf16_f32 v84, v84, v85
	v_cvt_pk_bf16_f32 v85, v86, v87
	v_pk_fma_f32 v[82:83], v[116:117], v[82:83], v[30:31]
	v_rsq_f32_e32 v86, v81
	v_pk_fma_f32 v[94:95], v[120:121], v[94:95], v[26:27]
	v_pk_fma_f32 v[92:93], v[122:123], v[92:93], v[24:25]
	v_cvt_pk_bf16_f32 v81, v82, v83
	v_mov_b32_e32 v82, v140
	v_mov_b32_e32 v83, v138
	v_mov_b32_e32 v138, v141
	v_cvt_pk_bf16_f32 v92, v92, v93
	v_cvt_pk_bf16_f32 v93, v94, v95
	v_add_u32_e32 v94, s25, v97
	v_pk_add_f32 v[82:83], v[82:83], v[138:139]
	global_store_dwordx2 v[142:143], v[84:85], off offset:1024
	ds_write2st64_b64 v94, v[84:85], v[80:81] offset0:2 offset1:3
	ds_bpermute_b32 v85, v125, v83
	ds_bpermute_b32 v84, v125, v82
	global_store_dwordx2 v[142:143], v[80:81], off offset:1536
	v_mul_f32_e32 v80, 0x45800000, v86
	v_cndmask_b32_e32 v80, v86, v80, vcc
	v_pk_mul_f32 v[76:77], v[76:77], v[80:81] op_sel_hi:[1,0]
	v_pk_mul_f32 v[78:79], v[78:79], v[80:81] op_sel_hi:[1,0]
	v_pk_fma_f32 v[76:77], v[122:123], v[76:77], v[24:25]
	v_pk_fma_f32 v[78:79], v[120:121], v[78:79], v[26:27]
	v_cvt_pk_bf16_f32 v76, v76, v77
	v_cvt_pk_bf16_f32 v77, v78, v79
	s_waitcnt lgkmcnt(0)
	v_pk_add_f32 v[78:79], v[82:83], v[84:85]
	ds_bpermute_b32 v83, v126, v79
	ds_bpermute_b32 v82, v126, v78
	v_pk_mul_f32 v[72:73], v[72:73], v[80:81] op_sel_hi:[1,0]
	v_pk_mul_f32 v[74:75], v[74:75], v[80:81] op_sel_hi:[1,0]
	v_pk_fma_f32 v[72:73], v[114:115], v[72:73], v[20:21]
	v_pk_fma_f32 v[74:75], v[110:111], v[74:75], v[22:23]
	s_waitcnt lgkmcnt(0)
	v_pk_add_f32 v[78:79], v[78:79], v[82:83]
	ds_bpermute_b32 v83, v127, v79
	ds_bpermute_b32 v82, v127, v78
	v_cvt_pk_bf16_f32 v72, v72, v73
	v_cvt_pk_bf16_f32 v73, v74, v75
	v_add_u32_e32 v81, 16, v94
	global_store_dwordx2 v[142:143], v[72:73], off offset:2560
	ds_write2st64_b64 v81, v[76:77], v[72:73] offset0:4 offset1:5
	s_waitcnt lgkmcnt(1)
	v_pk_add_f32 v[72:73], v[78:79], v[82:83]
	ds_bpermute_b32 v75, v128, v73
	ds_bpermute_b32 v74, v128, v72
	v_pk_mul_f32 v[68:69], v[68:69], v[80:81] op_sel_hi:[1,0]
	v_pk_mul_f32 v[70:71], v[70:71], v[80:81] op_sel_hi:[1,0]
	v_pk_fma_f32 v[68:69], v[112:113], v[68:69], v[16:17]
	v_pk_fma_f32 v[70:71], v[108:109], v[70:71], v[18:19]
	s_waitcnt lgkmcnt(0)
	v_pk_add_f32 v[72:73], v[72:73], v[74:75]
	ds_bpermute_b32 v75, v129, v73
	ds_bpermute_b32 v74, v129, v72
	v_cvt_pk_bf16_f32 v68, v68, v69
	v_cvt_pk_bf16_f32 v69, v70, v71
	v_pk_mul_f32 v[64:65], v[64:65], v[80:81] op_sel_hi:[1,0]
	v_pk_mul_f32 v[66:67], v[66:67], v[80:81] op_sel_hi:[1,0]
	s_waitcnt lgkmcnt(0)
	v_pk_add_f32 v[70:71], v[72:73], v[74:75]
	ds_bpermute_b32 v73, v130, v71
	ds_bpermute_b32 v72, v130, v70
	v_pk_fma_f32 v[64:65], v[118:119], v[64:65], v[28:29]
	v_pk_fma_f32 v[66:67], v[116:117], v[66:67], v[30:31]
	v_cvt_pk_bf16_f32 v64, v64, v65
	v_pk_mul_f32 v[88:89], v[88:89], v[144:145] op_sel_hi:[1,0]
	s_waitcnt lgkmcnt(0)
	v_pk_add_f32 v[70:71], v[70:71], v[72:73]
	v_pk_mul_f32 v[90:91], v[90:91], v[144:145] op_sel_hi:[1,0]
	v_pk_fma_f32 v[70:71], v[70:71], s[16:17], v[136:137] op_sel_hi:[1,0,0]
	v_pk_fma_f32 v[90:91], v[110:111], v[90:91], v[22:23]
	v_mul_f32_e32 v65, 0x4b800000, v71
	v_cmp_gt_f32_e32 vcc, s28, v71
	v_pk_fma_f32 v[88:89], v[114:115], v[88:89], v[20:21]
	global_store_dwordx2 v[142:143], v[92:93], off
	v_cndmask_b32_e32 v65, v71, v65, vcc
	v_rsq_f32_e32 v71, v65
	v_cvt_pk_bf16_f32 v65, v66, v67
	global_store_dwordx2 v[142:143], v[64:65], off offset:3584
	ds_write2st64_b64 v81, v[68:69], v[64:65] offset0:6 offset1:7
	v_mul_f32_e32 v64, 0x45800000, v71
	v_cndmask_b32_e32 v64, v71, v64, vcc
	v_pk_mul_f32 v[60:61], v[60:61], v[64:65] op_sel_hi:[1,0]
	v_pk_mul_f32 v[62:63], v[62:63], v[64:65] op_sel_hi:[1,0]
	v_pk_fma_f32 v[60:61], v[122:123], v[60:61], v[24:25]
	v_pk_fma_f32 v[62:63], v[120:121], v[62:63], v[26:27]
	v_cvt_pk_bf16_f32 v60, v60, v61
	v_cvt_pk_bf16_f32 v61, v62, v63
	v_add_co_u32_e32 v62, vcc, s27, v142
	v_pk_mul_f32 v[48:49], v[48:49], v[64:65] op_sel_hi:[1,0]
	s_nop 0
	v_addc_co_u32_e32 v63, vcc, 0, v143, vcc
	v_pk_fma_f32 v[48:49], v[118:119], v[48:49], v[28:29]
	v_pk_mul_f32 v[52:53], v[52:53], v[64:65] op_sel_hi:[1,0]
	v_pk_mul_f32 v[54:55], v[54:55], v[64:65] op_sel_hi:[1,0]
	v_cvt_pk_bf16_f32 v48, v48, v49
	v_mul_f32_e32 v49, 0x4b800000, v70
	v_cmp_gt_f32_e32 vcc, s28, v70
	v_pk_fma_f32 v[54:55], v[108:109], v[54:55], v[18:19]
	v_pk_fma_f32 v[52:53], v[112:113], v[52:53], v[16:17]
	v_cndmask_b32_e32 v49, v70, v49, vcc
	v_cvt_pk_bf16_f32 v52, v52, v53
	v_cvt_pk_bf16_f32 v53, v54, v55
	v_rsq_f32_e32 v54, v49
	v_pk_mul_f32 v[56:57], v[56:57], v[64:65] op_sel_hi:[1,0]
	v_pk_mul_f32 v[58:59], v[58:59], v[64:65] op_sel_hi:[1,0]
	v_pk_mul_f32 v[50:51], v[50:51], v[64:65] op_sel_hi:[1,0]
	v_pk_fma_f32 v[58:59], v[110:111], v[58:59], v[22:23]
	v_pk_fma_f32 v[56:57], v[114:115], v[56:57], v[20:21]
	v_pk_fma_f32 v[50:51], v[116:117], v[50:51], v[30:31]
	v_cvt_pk_bf16_f32 v56, v56, v57
	v_cvt_pk_bf16_f32 v57, v58, v59
	v_add_u32_e32 v58, 32, v94
	v_cvt_pk_bf16_f32 v49, v50, v51
	global_store_dwordx2 v[62:63], v[48:49], off offset:1536
	ds_write2st64_b64 v58, v[52:53], v[48:49] offset0:10 offset1:11
	v_mul_f32_e32 v48, 0x45800000, v54
	v_cndmask_b32_e32 v48, v54, v48, vcc
	v_pk_mul_f32 v[44:45], v[44:45], v[48:49] op_sel_hi:[1,0]
	v_pk_mul_f32 v[46:47], v[46:47], v[48:49] op_sel_hi:[1,0]
	v_pk_mul_f32 v[40:41], v[40:41], v[48:49] op_sel_hi:[1,0]
	v_pk_mul_f32 v[42:43], v[42:43], v[48:49] op_sel_hi:[1,0]
	v_pk_mul_f32 v[36:37], v[36:37], v[48:49] op_sel_hi:[1,0]
	v_pk_mul_f32 v[38:39], v[38:39], v[48:49] op_sel_hi:[1,0]
	v_pk_mul_f32 v[32:33], v[32:33], v[48:49] op_sel_hi:[1,0]
	v_pk_mul_f32 v[34:35], v[34:35], v[48:49] op_sel_hi:[1,0]
	v_pk_fma_f32 v[46:47], v[120:121], v[46:47], v[26:27]
	v_pk_fma_f32 v[44:45], v[122:123], v[44:45], v[24:25]
	v_pk_fma_f32 v[42:43], v[110:111], v[42:43], v[22:23]
	v_pk_fma_f32 v[40:41], v[114:115], v[40:41], v[20:21]
	v_pk_fma_f32 v[38:39], v[108:109], v[38:39], v[18:19]
	v_pk_fma_f32 v[36:37], v[112:113], v[36:37], v[16:17]
	v_pk_fma_f32 v[34:35], v[116:117], v[34:35], v[30:31]
	v_pk_fma_f32 v[32:33], v[118:119], v[32:33], v[28:29]
	v_cvt_pk_bf16_f32 v88, v88, v89
	v_cvt_pk_bf16_f32 v89, v90, v91
	v_cvt_pk_bf16_f32 v44, v44, v45
	v_cvt_pk_bf16_f32 v45, v46, v47
	v_cvt_pk_bf16_f32 v40, v40, v41
	v_cvt_pk_bf16_f32 v41, v42, v43
	v_add_u32_e32 v42, 48, v94
	v_cvt_pk_bf16_f32 v36, v36, v37
	v_cvt_pk_bf16_f32 v37, v38, v39
	v_cvt_pk_bf16_f32 v32, v32, v33
	v_cvt_pk_bf16_f32 v33, v34, v35
	global_store_dwordx2 v[142:143], v[88:89], off offset:512
	ds_write2st64_b64 v94, v[92:93], v[88:89] offset1:1
	global_store_dwordx2 v[142:143], v[76:77], off offset:2048
	global_store_dwordx2 v[142:143], v[68:69], off offset:3072
	global_store_dwordx2 v[62:63], v[60:61], off
	global_store_dwordx2 v[62:63], v[56:57], off offset:512
	ds_write2st64_b64 v58, v[60:61], v[56:57] offset0:8 offset1:9
	global_store_dwordx2 v[62:63], v[52:53], off offset:1024
	global_store_dwordx2 v[62:63], v[44:45], off offset:2048
	global_store_dwordx2 v[62:63], v[40:41], off offset:2560
	ds_write2st64_b64 v42, v[44:45], v[40:41] offset0:12 offset1:13
	global_store_dwordx2 v[62:63], v[36:37], off offset:3072
	global_store_dwordx2 v[62:63], v[32:33], off offset:3584
	ds_write2st64_b64 v42, v[36:37], v[32:33] offset0:14 offset1:15
	s_waitcnt lgkmcnt(0)
	v_mov_b32_e32 v32, 0
	v_mov_b32_e32 v33, v32
	v_mov_b32_e32 v34, v32
	v_mov_b32_e32 v35, v32

.LBB0_133:
	ds_read_b128 v[154:157], v151
	ds_read_b128 v[158:161], v151 offset:1024
	ds_read_b128 v[162:165], v151 offset:2048
	ds_read_b128 v[166:169], v151 offset:3072
	s_add_u32 s34, s24, 0xfffc0080
	s_addc_u32 s35, s25, -1
	s_cmp_eq_u32 s91, 12
	s_cselect_b32 s57, s15, s35
	s_cselect_b32 s56, s17, s34
	s_cselect_b32 s53, s9, s90
	s_cselect_b32 s52, s19, s89
	v_lshl_add_u64 v[146:147], s[24:25], 0, v[138:139]
	s_add_i32 m0, s29, 0xc000
	ds_read_b128 v[170:173], v152
	ds_read_b128 v[174:177], v152 offset:1024
	ds_read_b128 v[178:181], v152 offset:2048
	ds_read_b128 v[182:185], v152 offset:3072
	ds_read_b128 v[186:189], v152 offset:4096
	ds_read_b128 v[190:193], v152 offset:5120
	ds_read_b128 v[196:199], v152 offset:6144
	ds_read_b128 v[200:203], v152 offset:7168
	global_load_lds_dwordx4 v[146:147], off
	v_lshl_add_u64 v[146:147], s[24:25], 0, v[140:141]
	s_add_i32 m0, s29, 0xe000
	s_nop 0
	global_load_lds_dwordx4 v[146:147], off
	s_waitcnt lgkmcnt(8)
	s_barrier
	s_waitcnt lgkmcnt(0)
	s_setprio 1
	s_waitcnt lgkmcnt(0)
	v_mfma_f32_16x16x32_bf16 v[92:95], v[154:157], v[170:173], v[92:95]
	v_mfma_f32_16x16x32_bf16 v[84:87], v[162:165], v[170:173], v[84:87]
	v_mfma_f32_16x16x32_bf16 v[76:79], v[154:157], v[178:181], v[76:79]
	v_mfma_f32_16x16x32_bf16 v[72:75], v[162:165], v[178:181], v[72:75]
	v_mfma_f32_16x16x32_bf16 v[64:67], v[154:157], v[186:189], v[64:67]
	v_mfma_f32_16x16x32_bf16 v[56:59], v[162:165], v[186:189], v[56:59]
	v_mfma_f32_16x16x32_bf16 v[52:55], v[154:157], v[196:199], v[52:55]
	v_mfma_f32_16x16x32_bf16 v[48:51], v[162:165], v[196:199], v[48:51]
	v_mfma_f32_16x16x32_bf16 v[92:95], v[158:161], v[174:177], v[92:95]
	v_mfma_f32_16x16x32_bf16 v[84:87], v[166:169], v[174:177], v[84:87]
	v_mfma_f32_16x16x32_bf16 v[76:79], v[158:161], v[182:185], v[76:79]
	v_mfma_f32_16x16x32_bf16 v[72:75], v[166:169], v[182:185], v[72:75]
	v_mfma_f32_16x16x32_bf16 v[64:67], v[158:161], v[190:193], v[64:67]
	v_mfma_f32_16x16x32_bf16 v[56:59], v[166:169], v[190:193], v[56:59]
	v_mfma_f32_16x16x32_bf16 v[52:55], v[158:161], v[200:203], v[52:55]
	v_mfma_f32_16x16x32_bf16 v[48:51], v[166:169], v[200:203], v[48:51]
	s_setprio 0
	s_barrier
	s_add_i32 s34, s58, s28
	v_lshl_add_u64 v[146:147], s[52:53], 0, v[132:133]
	s_mov_b32 m0, s34
	ds_read_b128 v[204:207], v153
	ds_read_b128 v[208:211], v153 offset:1024
	ds_read_b128 v[212:215], v153 offset:2048
	ds_read_b128 v[216:219], v153 offset:3072
	global_load_lds_dwordx4 v[146:147], off
	v_lshl_add_u64 v[220:221], s[52:53], 0, v[128:129]
	s_add_i32 m0, s34, 0x2000
	s_nop 0
	global_load_lds_dwordx4 v[220:221], off
	s_barrier
	s_waitcnt lgkmcnt(0)
	s_setprio 1
	s_waitcnt lgkmcnt(0)
	v_mfma_f32_16x16x32_bf16 v[124:127], v[204:207], v[170:173], v[124:127]
	v_mfma_f32_16x16x32_bf16 v[120:123], v[212:215], v[170:173], v[120:123]
	v_mfma_f32_16x16x32_bf16 v[116:119], v[204:207], v[178:181], v[116:119]
	v_mfma_f32_16x16x32_bf16 v[112:115], v[212:215], v[178:181], v[112:115]
	v_mfma_f32_16x16x32_bf16 v[108:111], v[204:207], v[186:189], v[108:111]
	v_mfma_f32_16x16x32_bf16 v[104:107], v[212:215], v[186:189], v[104:107]
	v_mfma_f32_16x16x32_bf16 v[100:103], v[204:207], v[196:199], v[100:103]
	v_mfma_f32_16x16x32_bf16 v[96:99], v[212:215], v[196:199], v[96:99]
	v_mfma_f32_16x16x32_bf16 v[124:127], v[208:211], v[174:177], v[124:127]
	v_mfma_f32_16x16x32_bf16 v[120:123], v[216:219], v[174:177], v[120:123]
	v_mfma_f32_16x16x32_bf16 v[116:119], v[208:211], v[182:185], v[116:119]
	v_mfma_f32_16x16x32_bf16 v[112:115], v[216:219], v[182:185], v[112:115]
	v_mfma_f32_16x16x32_bf16 v[108:111], v[208:211], v[190:193], v[108:111]
	v_mfma_f32_16x16x32_bf16 v[104:107], v[216:219], v[190:193], v[104:107]
	v_mfma_f32_16x16x32_bf16 v[100:103], v[208:211], v[200:203], v[100:103]
	v_mfma_f32_16x16x32_bf16 v[96:99], v[216:219], v[200:203], v[96:99]
	s_setprio 0
	s_mov_b32 m0, s29
	v_lshl_add_u64 v[222:223], s[56:57], 0, v[134:135]
	s_barrier
	ds_read_b128 v[170:173], v152 offset:16384
	ds_read_b128 v[174:177], v152 offset:17408
	ds_read_b128 v[178:181], v152 offset:18432
	ds_read_b128 v[182:185], v152 offset:19456
	ds_read_b128 v[186:189], v152 offset:20480
	ds_read_b128 v[190:193], v152 offset:21504
	ds_read_b128 v[196:199], v152 offset:22528
	ds_read_b128 v[200:203], v152 offset:23552
	global_load_lds_dwordx4 v[222:223], off
	v_lshl_add_u64 v[224:225], s[56:57], 0, v[130:131]
	s_mov_b32 m0, s30
	s_nop 0
	global_load_lds_dwordx4 v[224:225], off
	s_barrier
	s_waitcnt lgkmcnt(0)
	s_setprio 1
	s_waitcnt lgkmcnt(0)
	v_mfma_f32_16x16x32_bf16 v[32:35], v[154:157], v[170:173], v[32:35]
	v_mfma_f32_16x16x32_bf16 v[24:27], v[162:165], v[170:173], v[24:27]
	v_mfma_f32_16x16x32_bf16 v[20:23], v[154:157], v[178:181], v[20:23]
	v_mfma_f32_16x16x32_bf16 v[16:19], v[162:165], v[178:181], v[16:19]
	v_mfma_f32_16x16x32_bf16 v[12:15], v[154:157], v[186:189], v[12:15]
	v_mfma_f32_16x16x32_bf16 v[8:11], v[162:165], v[186:189], v[8:11]
	v_mfma_f32_16x16x32_bf16 v[4:7], v[154:157], v[196:199], v[4:7]
	v_mfma_f32_16x16x32_bf16 v[0:3], v[162:165], v[196:199], v[0:3]
	v_mfma_f32_16x16x32_bf16 v[32:35], v[158:161], v[174:177], v[32:35]
	v_mfma_f32_16x16x32_bf16 v[24:27], v[166:169], v[174:177], v[24:27]
	v_mfma_f32_16x16x32_bf16 v[20:23], v[158:161], v[182:185], v[20:23]
	v_mfma_f32_16x16x32_bf16 v[16:19], v[166:169], v[182:185], v[16:19]
	v_mfma_f32_16x16x32_bf16 v[12:15], v[158:161], v[190:193], v[12:15]
	v_mfma_f32_16x16x32_bf16 v[8:11], v[166:169], v[190:193], v[8:11]
	v_mfma_f32_16x16x32_bf16 v[4:7], v[158:161], v[200:203], v[4:7]
	v_mfma_f32_16x16x32_bf16 v[0:3], v[166:169], v[200:203], v[0:3]
	s_setprio 0
	s_barrier
	s_add_u32 s34, s52, 0x40000
	s_addc_u32 s35, s53, 0
	s_add_i32 s60, s59, s28
	v_lshl_add_u64 v[154:155], s[34:35], 0, v[132:133]
	s_mov_b32 m0, s60
	s_nop 0
	global_load_lds_dwordx4 v[154:155], off
	v_lshl_add_u64 v[154:155], s[34:35], 0, v[128:129]
	s_add_i32 m0, s60, 0x2000
	s_nop 0
	global_load_lds_dwordx4 v[154:155], off
	s_waitcnt vmcnt(6)
	s_barrier
	s_setprio 1
	v_mfma_f32_16x16x32_bf16 v[88:91], v[204:207], v[170:173], v[88:91]
	v_mfma_f32_16x16x32_bf16 v[80:83], v[212:215], v[170:173], v[80:83]
	v_mfma_f32_16x16x32_bf16 v[68:71], v[204:207], v[178:181], v[68:71]
	v_mfma_f32_16x16x32_bf16 v[60:63], v[212:215], v[178:181], v[60:63]
	v_mfma_f32_16x16x32_bf16 v[44:47], v[204:207], v[186:189], v[44:47]
	v_mfma_f32_16x16x32_bf16 v[40:43], v[212:215], v[186:189], v[40:43]
	v_mfma_f32_16x16x32_bf16 v[36:39], v[204:207], v[196:199], v[36:39]
	v_mfma_f32_16x16x32_bf16 v[28:31], v[212:215], v[196:199], v[28:31]
	v_mfma_f32_16x16x32_bf16 v[88:91], v[208:211], v[174:177], v[88:91]
	v_mfma_f32_16x16x32_bf16 v[80:83], v[216:219], v[174:177], v[80:83]
	v_mfma_f32_16x16x32_bf16 v[68:71], v[208:211], v[182:185], v[68:71]
	v_mfma_f32_16x16x32_bf16 v[60:63], v[216:219], v[182:185], v[60:63]
	v_mfma_f32_16x16x32_bf16 v[44:47], v[208:211], v[190:193], v[44:47]
	v_mfma_f32_16x16x32_bf16 v[40:43], v[216:219], v[190:193], v[40:43]
	v_mfma_f32_16x16x32_bf16 v[36:39], v[208:211], v[200:203], v[36:39]
	v_mfma_f32_16x16x32_bf16 v[28:31], v[216:219], v[200:203], v[28:31]
	s_setprio 0
	s_add_i32 s60, 0, 0x18000
	v_add_u32_e32 v166, s60, v149
	s_barrier
	ds_read_b128 v[154:157], v166
	ds_read_b128 v[158:161], v166 offset:1024
	ds_read_b128 v[162:165], v166 offset:2048
	ds_read_b128 v[166:169], v166 offset:3072
	s_add_u32 s34, s56, 0x40000
	s_addc_u32 s35, s57, 0
	s_mov_b32 m0, s31
	v_lshl_add_u64 v[204:205], s[34:35], 0, v[134:135]
	ds_read_b128 v[170:173], v152 offset:32768
	ds_read_b128 v[174:177], v152 offset:33792
	ds_read_b128 v[178:181], v152 offset:34816
	ds_read_b128 v[182:185], v152 offset:35840
	ds_read_b128 v[186:189], v152 offset:36864
	ds_read_b128 v[190:193], v152 offset:37888
	ds_read_b128 v[196:199], v152 offset:38912
	ds_read_b128 v[200:203], v152 offset:39936
	global_load_lds_dwordx4 v[204:205], off
	v_lshl_add_u64 v[204:205], s[34:35], 0, v[130:131]
	s_mov_b32 m0, s33
	s_nop 0
	global_load_lds_dwordx4 v[204:205], off
	s_waitcnt lgkmcnt(8)
	s_barrier
	s_waitcnt lgkmcnt(0)
	s_setprio 1
	s_waitcnt lgkmcnt(0)
	v_mfma_f32_16x16x32_bf16 v[92:95], v[154:157], v[170:173], v[92:95]
	v_mfma_f32_16x16x32_bf16 v[84:87], v[162:165], v[170:173], v[84:87]
	v_mfma_f32_16x16x32_bf16 v[76:79], v[154:157], v[178:181], v[76:79]
	v_mfma_f32_16x16x32_bf16 v[72:75], v[162:165], v[178:181], v[72:75]
	v_mfma_f32_16x16x32_bf16 v[64:67], v[154:157], v[186:189], v[64:67]
	v_mfma_f32_16x16x32_bf16 v[56:59], v[162:165], v[186:189], v[56:59]
	v_mfma_f32_16x16x32_bf16 v[52:55], v[154:157], v[196:199], v[52:55]
	v_mfma_f32_16x16x32_bf16 v[48:51], v[162:165], v[196:199], v[48:51]
	v_mfma_f32_16x16x32_bf16 v[92:95], v[158:161], v[174:177], v[92:95]
	v_mfma_f32_16x16x32_bf16 v[84:87], v[166:169], v[174:177], v[84:87]
	v_mfma_f32_16x16x32_bf16 v[76:79], v[158:161], v[182:185], v[76:79]
	v_mfma_f32_16x16x32_bf16 v[72:75], v[166:169], v[182:185], v[72:75]
	v_mfma_f32_16x16x32_bf16 v[64:67], v[158:161], v[190:193], v[64:67]
	v_mfma_f32_16x16x32_bf16 v[56:59], v[166:169], v[190:193], v[56:59]
	v_mfma_f32_16x16x32_bf16 v[52:55], v[158:161], v[200:203], v[52:55]
	v_mfma_f32_16x16x32_bf16 v[48:51], v[166:169], v[200:203], v[48:51]
	s_setprio 0
	s_barrier
	s_add_i32 s56, 0, 0x1c000
	s_add_i32 s34, s60, s28
	v_add_u32_e32 v195, s56, v149
	v_lshl_add_u64 v[146:147], v[146:147], 0, s[10:11]
	s_mov_b32 m0, s34
	ds_read_b128 v[204:207], v195
	ds_read_b128 v[208:211], v195 offset:1024
	ds_read_b128 v[212:215], v195 offset:2048
	ds_read_b128 v[216:219], v195 offset:3072
	global_load_lds_dwordx4 v[146:147], off
	v_lshl_add_u64 v[146:147], v[220:221], 0, s[10:11]
	s_add_i32 m0, s34, 0x2000
	s_nop 0
	global_load_lds_dwordx4 v[146:147], off
	s_barrier
	s_waitcnt lgkmcnt(0)
	s_setprio 1
	s_waitcnt lgkmcnt(0)
	v_mfma_f32_16x16x32_bf16 v[124:127], v[204:207], v[170:173], v[124:127]
	v_mfma_f32_16x16x32_bf16 v[120:123], v[212:215], v[170:173], v[120:123]
	v_mfma_f32_16x16x32_bf16 v[116:119], v[204:207], v[178:181], v[116:119]
	v_mfma_f32_16x16x32_bf16 v[112:115], v[212:215], v[178:181], v[112:115]
	v_mfma_f32_16x16x32_bf16 v[108:111], v[204:207], v[186:189], v[108:111]
	v_mfma_f32_16x16x32_bf16 v[104:107], v[212:215], v[186:189], v[104:107]
	v_mfma_f32_16x16x32_bf16 v[100:103], v[204:207], v[196:199], v[100:103]
	v_mfma_f32_16x16x32_bf16 v[96:99], v[212:215], v[196:199], v[96:99]
	v_mfma_f32_16x16x32_bf16 v[124:127], v[208:211], v[174:177], v[124:127]
	v_mfma_f32_16x16x32_bf16 v[120:123], v[216:219], v[174:177], v[120:123]
	v_mfma_f32_16x16x32_bf16 v[116:119], v[208:211], v[182:185], v[116:119]
	v_mfma_f32_16x16x32_bf16 v[112:115], v[216:219], v[182:185], v[112:115]
	v_mfma_f32_16x16x32_bf16 v[108:111], v[208:211], v[190:193], v[108:111]
	v_mfma_f32_16x16x32_bf16 v[104:107], v[216:219], v[190:193], v[104:107]
	v_mfma_f32_16x16x32_bf16 v[100:103], v[208:211], v[200:203], v[100:103]
	v_mfma_f32_16x16x32_bf16 v[96:99], v[216:219], v[200:203], v[96:99]
	s_setprio 0
	s_mov_b32 m0, s42
	v_lshl_add_u64 v[146:147], v[222:223], 0, s[10:11]
	s_barrier
	ds_read_b128 v[170:173], v152 offset:49152
	ds_read_b128 v[174:177], v152 offset:50176
	ds_read_b128 v[178:181], v152 offset:51200
	ds_read_b128 v[182:185], v152 offset:52224
	ds_read_b128 v[186:189], v152 offset:53248
	ds_read_b128 v[190:193], v152 offset:54272
	ds_read_b128 v[196:199], v152 offset:55296
	ds_read_b128 v[200:203], v152 offset:56320
	global_load_lds_dwordx4 v[146:147], off
	v_lshl_add_u64 v[146:147], v[224:225], 0, s[10:11]
	s_mov_b32 m0, s43
	s_nop 0
	global_load_lds_dwordx4 v[146:147], off
	s_barrier
	s_waitcnt lgkmcnt(0)
	s_setprio 1
	s_waitcnt lgkmcnt(0)
	v_mfma_f32_16x16x32_bf16 v[32:35], v[154:157], v[170:173], v[32:35]
	v_mfma_f32_16x16x32_bf16 v[24:27], v[162:165], v[170:173], v[24:27]
	v_mfma_f32_16x16x32_bf16 v[20:23], v[154:157], v[178:181], v[20:23]
	v_mfma_f32_16x16x32_bf16 v[16:19], v[162:165], v[178:181], v[16:19]
	v_mfma_f32_16x16x32_bf16 v[12:15], v[154:157], v[186:189], v[12:15]
	v_mfma_f32_16x16x32_bf16 v[8:11], v[162:165], v[186:189], v[8:11]
	v_mfma_f32_16x16x32_bf16 v[4:7], v[154:157], v[196:199], v[4:7]
	v_mfma_f32_16x16x32_bf16 v[0:3], v[162:165], v[196:199], v[0:3]
	v_mfma_f32_16x16x32_bf16 v[32:35], v[158:161], v[174:177], v[32:35]
	v_mfma_f32_16x16x32_bf16 v[24:27], v[166:169], v[174:177], v[24:27]
	v_mfma_f32_16x16x32_bf16 v[20:23], v[158:161], v[182:185], v[20:23]
	v_mfma_f32_16x16x32_bf16 v[16:19], v[166:169], v[182:185], v[16:19]
	v_mfma_f32_16x16x32_bf16 v[12:15], v[158:161], v[190:193], v[12:15]
	v_mfma_f32_16x16x32_bf16 v[8:11], v[166:169], v[190:193], v[8:11]
	v_mfma_f32_16x16x32_bf16 v[4:7], v[158:161], v[200:203], v[4:7]
	v_mfma_f32_16x16x32_bf16 v[0:3], v[166:169], v[200:203], v[0:3]
	s_setprio 0
	s_barrier
	s_add_u32 s34, s52, 0x40080
	s_addc_u32 s35, s53, 0
	s_add_i32 s52, s56, s28
	v_lshl_add_u64 v[146:147], s[34:35], 0, v[132:133]
	s_mov_b32 m0, s52
	s_nop 0
	global_load_lds_dwordx4 v[146:147], off
	v_lshl_add_u64 v[146:147], s[34:35], 0, v[128:129]
	s_add_i32 m0, s52, 0x2000
	s_nop 0
	global_load_lds_dwordx4 v[146:147], off
	s_waitcnt vmcnt(6)
	s_barrier
	s_setprio 1
	v_mfma_f32_16x16x32_bf16 v[88:91], v[204:207], v[170:173], v[88:91]
	v_mfma_f32_16x16x32_bf16 v[80:83], v[212:215], v[170:173], v[80:83]
	v_mfma_f32_16x16x32_bf16 v[68:71], v[204:207], v[178:181], v[68:71]
	v_mfma_f32_16x16x32_bf16 v[60:63], v[212:215], v[178:181], v[60:63]
	v_mfma_f32_16x16x32_bf16 v[44:47], v[204:207], v[186:189], v[44:47]
	v_mfma_f32_16x16x32_bf16 v[40:43], v[212:215], v[186:189], v[40:43]
	v_mfma_f32_16x16x32_bf16 v[36:39], v[204:207], v[196:199], v[36:39]
	v_mfma_f32_16x16x32_bf16 v[28:31], v[212:215], v[196:199], v[28:31]
	v_mfma_f32_16x16x32_bf16 v[88:91], v[208:211], v[174:177], v[88:91]
	v_mfma_f32_16x16x32_bf16 v[80:83], v[216:219], v[174:177], v[80:83]
	v_mfma_f32_16x16x32_bf16 v[68:71], v[208:211], v[182:185], v[68:71]
	v_mfma_f32_16x16x32_bf16 v[60:63], v[216:219], v[182:185], v[60:63]
	v_mfma_f32_16x16x32_bf16 v[44:47], v[208:211], v[190:193], v[44:47]
	v_mfma_f32_16x16x32_bf16 v[40:43], v[216:219], v[190:193], v[40:43]
	v_mfma_f32_16x16x32_bf16 v[36:39], v[208:211], v[200:203], v[36:39]
	v_mfma_f32_16x16x32_bf16 v[28:31], v[216:219], v[200:203], v[28:31]
	s_setprio 0
	s_add_i32 s91, s91, 2
	s_add_u32 s24, s24, 0x100
	s_addc_u32 s25, s25, 0
	s_add_u32 s89, s89, 0x100
	s_addc_u32 s90, s90, 0
	s_cmp_gt_u32 s91, 13
	s_barrier
	s_cbranch_scc0 .LBB0_133
	v_lshl_add_u32 v146, s16, 8, v148
	s_cmp_lg_u32 s14, 18
	s_mov_b64 s[16:17], -1
	s_cbranch_scc0 .LBB0_136
	v_lshl_or_b32 v154, s14, 8, v150
	v_ashrrev_i32_e32 v155, 31, v154
	v_mov_b64_e32 v[158:159], s[26:27]
	v_mad_i64_i32 v[156:157], s[14:15], v146, s88, v[158:159]
	v_lshlrev_b64 v[160:161], 1, v[154:155]
	v_cvt_pk_bf16_f32 v124, v124, v125
	v_cvt_pk_bf16_f32 v125, v126, v127
	v_cvt_pk_bf16_f32 v126, v120, v121
	v_or_b32_e32 v120, 16, v146
	v_lshl_add_u64 v[162:163], v[156:157], 0, v[160:161]
	v_cvt_pk_bf16_f32 v127, v122, v123
	v_mad_i64_i32 v[120:121], s[14:15], v120, s88, v[158:159]
	v_cvt_pk_bf16_f32 v116, v116, v117
	v_cvt_pk_bf16_f32 v117, v118, v119
	v_cvt_pk_bf16_f32 v118, v112, v113
	v_or_b32_e32 v112, 32, v146
	global_store_dwordx4 v[162:163], v[124:127], off offset:256 nt
	v_cvt_pk_bf16_f32 v119, v114, v115
	v_mad_i64_i32 v[112:113], s[14:15], v112, s88, v[158:159]
	v_lshl_add_u64 v[124:125], v[120:121], 0, v[160:161]
	v_cvt_pk_bf16_f32 v108, v108, v109
	v_cvt_pk_bf16_f32 v109, v110, v111
	v_cvt_pk_bf16_f32 v110, v104, v105
	v_or_b32_e32 v104, 48, v146
	global_store_dwordx4 v[124:125], v[116:119], off offset:256 nt
	v_cvt_pk_bf16_f32 v111, v106, v107
	v_mad_i64_i32 v[104:105], s[14:15], v104, s88, v[158:159]
	v_lshl_add_u64 v[116:117], v[112:113], 0, v[160:161]
	v_cvt_pk_bf16_f32 v100, v100, v101
	v_cvt_pk_bf16_f32 v101, v102, v103
	v_cvt_pk_bf16_f32 v102, v96, v97
	v_add_u32_e32 v96, 0x80, v146
	global_store_dwordx4 v[116:117], v[108:111], off offset:256 nt
	v_cvt_pk_bf16_f32 v103, v98, v99
	v_mad_i64_i32 v[96:97], s[14:15], v96, s88, v[158:159]
	v_lshl_add_u64 v[108:109], v[104:105], 0, v[160:161]
	v_cvt_pk_bf16_f32 v88, v88, v89
	v_cvt_pk_bf16_f32 v89, v90, v91
	v_cvt_pk_bf16_f32 v90, v80, v81
	v_add_u32_e32 v80, 0x90, v146
	global_store_dwordx4 v[108:109], v[100:103], off offset:256 nt
	v_cvt_pk_bf16_f32 v91, v82, v83
	v_mad_i64_i32 v[80:81], s[14:15], v80, s88, v[158:159]
	v_lshl_add_u64 v[100:101], v[96:97], 0, v[160:161]
	v_cvt_pk_bf16_f32 v68, v68, v69
	v_cvt_pk_bf16_f32 v69, v70, v71
	v_cvt_pk_bf16_f32 v70, v60, v61
	v_add_u32_e32 v60, 0xa0, v146
	global_store_dwordx4 v[100:101], v[88:91], off offset:256 nt
	v_cvt_pk_bf16_f32 v71, v62, v63
	v_mad_i64_i32 v[60:61], s[14:15], v60, s88, v[158:159]
	v_lshl_add_u64 v[88:89], v[80:81], 0, v[160:161]
	v_cvt_pk_bf16_f32 v44, v44, v45
	v_cvt_pk_bf16_f32 v45, v46, v47
	v_cvt_pk_bf16_f32 v46, v40, v41
	v_add_u32_e32 v40, 0xb0, v146
	global_store_dwordx4 v[88:89], v[68:71], off offset:256 nt
	v_cvt_pk_bf16_f32 v47, v42, v43
	v_mad_i64_i32 v[40:41], s[14:15], v40, s88, v[158:159]
	v_lshl_add_u64 v[68:69], v[60:61], 0, v[160:161]
	v_cvt_pk_bf16_f32 v154, v92, v93
	v_cvt_pk_bf16_f32 v155, v94, v95
	v_cvt_pk_bf16_f32 v156, v84, v85
	v_cvt_pk_bf16_f32 v157, v86, v87
	v_cvt_pk_bf16_f32 v120, v76, v77
	v_cvt_pk_bf16_f32 v121, v78, v79
	v_cvt_pk_bf16_f32 v122, v72, v73
	v_cvt_pk_bf16_f32 v123, v74, v75
	v_cvt_pk_bf16_f32 v112, v64, v65
	v_cvt_pk_bf16_f32 v113, v66, v67
	v_cvt_pk_bf16_f32 v114, v56, v57
	v_cvt_pk_bf16_f32 v115, v58, v59
	v_cvt_pk_bf16_f32 v104, v52, v53
	v_cvt_pk_bf16_f32 v105, v54, v55
	v_cvt_pk_bf16_f32 v106, v48, v49
	v_cvt_pk_bf16_f32 v107, v50, v51
	v_cvt_pk_bf16_f32 v96, v32, v33
	v_cvt_pk_bf16_f32 v97, v34, v35
	v_cvt_pk_bf16_f32 v98, v24, v25
	v_cvt_pk_bf16_f32 v99, v26, v27
	v_cvt_pk_bf16_f32 v80, v20, v21
	v_cvt_pk_bf16_f32 v81, v22, v23
	v_cvt_pk_bf16_f32 v82, v16, v17
	v_cvt_pk_bf16_f32 v83, v18, v19
	v_cvt_pk_bf16_f32 v60, v12, v13
	v_cvt_pk_bf16_f32 v61, v14, v15
	v_cvt_pk_bf16_f32 v62, v8, v9
	v_cvt_pk_bf16_f32 v63, v10, v11
	global_store_dwordx4 v[68:69], v[44:47], off offset:256 nt
	v_cvt_pk_bf16_f32 v42, v0, v1
	v_cvt_pk_bf16_f32 v43, v2, v3
	v_lshl_add_u64 v[44:45], v[40:41], 0, v[160:161]
	v_cvt_pk_bf16_f32 v40, v4, v5
	v_cvt_pk_bf16_f32 v41, v6, v7
	v_cvt_pk_bf16_f32 v36, v36, v37
	v_cvt_pk_bf16_f32 v37, v38, v39
	v_cvt_pk_bf16_f32 v38, v28, v29
	v_cvt_pk_bf16_f32 v39, v30, v31
	global_store_dwordx4 v[162:163], v[154:157], off nt
	global_store_dwordx4 v[124:125], v[120:123], off nt
	global_store_dwordx4 v[116:117], v[112:115], off nt
	global_store_dwordx4 v[108:109], v[104:107], off nt
	global_store_dwordx4 v[100:101], v[96:99], off nt
	global_store_dwordx4 v[88:89], v[80:83], off nt
	global_store_dwordx4 v[68:69], v[60:63], off nt
	global_store_dwordx4 v[44:45], v[40:43], off nt
	global_store_dwordx4 v[44:45], v[36:39], off offset:256 nt
	s_mov_b64 s[16:17], 0

.LBB0_570:
	s_add_i32 s33, s34, 1
	s_cmp_ge_u32 s33, s55
	v_mov_b64_e32 v[162:163], v[164:165]
	s_cbranch_scc1 .LBB0_572
	v_mov_b32_e32 v66, v182
	s_bitcmp1_b32 s33, 0
	v_lshrrev_b32_e32 v64, 4, v66
	v_xor_b32_e32 v64, v64, v66
	v_ashrrev_i32_e32 v67, 4, v66
	v_lshlrev_b32_e32 v64, 3, v64
	v_and_b32_e32 v68, 24, v64
	v_add_u32_e32 v64, s59, v67
	v_xor_b32_e32 v64, v64, v66
	s_cselect_b32 s6, 0xe000, 0
	s_add_i32 s7, s77, s21
	v_lshlrev_b32_e32 v64, 3, v64
	s_add_i32 s6, s6, 0
	v_add_lshl_u32 v69, s7, v67, 9
	v_and_b32_e32 v64, 0x78, v64
	v_or3_b32 v152, v64, v69, s25
	s_add_i32 s42, s6, s39
	s_waitcnt lgkmcnt(0)
	v_lshl_add_u64 v[64:65], v[152:153], 1, s[52:53]
	s_mov_b32 m0, s42
	v_or_b32_e32 v152, 0x100, v152
	global_load_lds_dwordx4 v[64:65], off
	v_lshl_add_u64 v[64:65], v[152:153], 1, s[52:53]
	s_add_i32 m0, s42, 0x2000
	v_lshlrev_b32_e32 v70, 3, v66
	s_movk_i32 s7, 0xffe0
	global_load_lds_dwordx4 v[64:65], off
	v_and_or_b32 v64, v70, s7, v68
	v_add_u32_e32 v152, s20, v64
	v_lshl_add_u64 v[64:65], v[152:153], 1, s[10:11]
	s_add_i32 m0, s42, 0x4000
	s_add_i32 s6, s6, s83
	global_load_lds_dwordx4 v[64:65], off
	v_add_u32_e32 v64, s47, v67
	v_xor_b32_e32 v64, v64, v66
	v_lshlrev_b32_e32 v64, 3, v64
	v_and_or_b32 v64, v64, s89, v69
	v_add_u32_e32 v67, s25, v64
	v_add_u32_e32 v64, 0x800, v67
	v_mov_b32_e32 v65, v153
	v_lshl_add_u64 v[64:65], v[64:65], 1, s[52:53]
	s_mov_b32 m0, s6
	v_add_u32_e32 v152, 0x200, v152
	global_load_lds_dwordx4 v[64:65], off
	v_add_u32_e32 v64, 0x900, v67
	v_mov_b32_e32 v65, v153
	v_lshl_add_u64 v[64:65], v[64:65], 1, s[52:53]
	s_add_i32 m0, s6, 0x2000
	s_add_i32 s35, s21, 32
	global_load_lds_dwordx4 v[64:65], off
	v_lshl_add_u64 v[64:65], v[152:153], 1, s[10:11]
	s_add_i32 m0, s6, 0x4000
	s_add_i32 s64, s42, 0xa000
	global_load_lds_dwordx4 v[64:65], off
	v_ashrrev_i32_e32 v64, 2, v66
	v_add_u32_e32 v68, s21, v64
	v_and_b32_e32 v64, 24, v70
	v_add_u32_e32 v65, 32, v68
	v_or_b32_e32 v69, s30, v64
	v_or_b32_e32 v64, s31, v64
	v_lshl_add_u32 v152, v65, 10, v69
	v_mad_u64_u32 v[64:65], s[6:7], v65, s91, v[64:65]
	s_add_i32 m0, s42, 0x8000
	v_lshl_add_u64 v[66:67], v[152:153], 1, s[56:57]
	v_mov_b32_e32 v65, v153
	global_load_lds_dwordx4 v[66:67], off
	v_lshl_add_u64 v[66:67], v[64:65], 1, s[26:27]
	v_lshlrev_b32_e32 v65, 10, v68
	s_mov_b32 s6, 0xc000
	v_add3_u32 v152, v65, v69, s6
	s_lshr_b32 s6, s35, 1
	s_mov_b32 m0, s64
	s_and_b32 s6, s6, 0x7fffff0
	global_load_lds_dwordx4 v[66:67], off
	v_lshl_add_u64 v[66:67], v[152:153], 1, s[56:57]
	s_add_i32 m0, s42, 0x8400
	v_add_u32_e32 v152, 0x12000, v64
	s_add_i32 s6, s6, s12
	global_load_lds_dwordx4 v[66:67], off
	v_lshl_add_u64 v[64:65], v[152:153], 1, s[26:27]
	s_add_i32 m0, s42, 0xa400
	v_lshl_or_b32 v152, s6, 5, v183
	global_load_lds_dwordx4 v[64:65], off
	v_lshl_add_u64 v[64:65], v[152:153], 3, s[16:17]
	global_load_dwordx2 v[162:163], v[64:65], off

.LBB0_584:
	s_andn2_b32 s20, 1, s21
	s_mul_i32 s20, s20, 0xe000
	v_mov_b32_e32 v0, v182
	s_add_i32 s20, s50, s20
	v_lshrrev_b32_e32 v1, 2, v0
	v_lshl_add_u32 v8, v0, 4, s20
	v_lshlrev_b32_e32 v0, 3, v0
	v_add_u32_e32 v5, s7, v1
	v_and_or_b32 v4, v0, 24, s6
	ds_read_b128 v[0:3], v8 offset:49152
	ds_read_b128 v[216:219], v8 offset:50176
	v_mad_u64_u32 v[4:5], s[30:31], v5, s91, v[4:5]
	v_add_u32_e32 v152, 0xfffb8000, v4
	v_lshl_add_u64 v[6:7], v[152:153], 1, s[26:27]
	v_add_u32_e32 v152, 0xfffca000, v4
	v_lshl_add_u64 v[4:5], v[152:153], 1, s[26:27]
	s_waitcnt lgkmcnt(1)
	global_store_dwordx4 v[6:7], v[0:3], off
	s_waitcnt lgkmcnt(0)
	global_store_dwordx4 v[4:5], v[216:219], off
	s_waitcnt lgkmcnt(0)

.LBB0_587:
	v_mov_b32_e32 v108, v182
	s_bitcmp1_b32 s21, 0
	s_cselect_b32 s21, 0xe000, 0
	v_bfe_u32 v109, v108, 3, 2
	v_and_or_b32 v0, v108, 4, v109
	v_and_b32_e32 v1, 3, v108
	s_add_i32 s21, s21, 0
	v_and_b32_e32 v102, 31, v108
	v_ashrrev_i32_e32 v103, 5, v108
	v_lshl_or_b32 v110, v0, 2, v1
	s_setprio 3
	v_lshl_add_u32 v111, v110, 8, s21
	s_waitcnt lgkmcnt(0)
	v_bitop3_b32 v248, v110, v103, 15 bitop3:0x6c
	v_lshl_add_u32 v248, v248, 4, v111
	ds_read_b128 v[216:219], v248 offset:24576
	v_add_u32_e32 v248, 2, v103
	v_bitop3_b32 v248, v110, v248, 15 bitop3:0x6c
	v_lshl_add_u32 v248, v248, 4, v111
	ds_read_b128 v[220:223], v248 offset:24576
	v_add_u32_e32 v248, 4, v103
	v_bitop3_b32 v248, v110, v248, 15 bitop3:0x6c
	v_lshl_add_u32 v248, v248, 4, v111
	ds_read_b128 v[224:227], v248 offset:24576
	v_add_u32_e32 v248, 6, v103
	v_bitop3_b32 v248, v110, v248, 15 bitop3:0x6c
	v_lshl_add_u32 v248, v248, 4, v111
	ds_read_b128 v[228:231], v248 offset:24576
	v_add_u32_e32 v248, 8, v103
	v_bitop3_b32 v248, v110, v248, 15 bitop3:0x6c
	v_lshl_add_u32 v248, v248, 4, v111
	ds_read_b128 v[232:235], v248 offset:24576
	v_add_u32_e32 v248, 10, v103
	v_bitop3_b32 v248, v110, v248, 15 bitop3:0x6c
	v_lshl_add_u32 v248, v248, 4, v111
	ds_read_b128 v[236:239], v248 offset:24576
	v_add_u32_e32 v248, 12, v103
	v_bitop3_b32 v248, v110, v248, 15 bitop3:0x6c
	v_lshl_add_u32 v248, v248, 4, v111
	ds_read_b128 v[240:243], v248 offset:24576
	v_add_u32_e32 v248, 14, v103
	v_bitop3_b32 v248, v110, v248, 15 bitop3:0x6c
	v_lshl_add_u32 v248, v248, 4, v111
	ds_read_b128 v[244:247], v248 offset:24576
	s_waitcnt lgkmcnt(7)
	v_mfma_f32_32x32x16_bf16 v[16:31], v[216:219], v[32:35], 0
	v_mfma_f32_32x32x16_bf16 v[0:15], v[216:219], v[64:67], 0
	s_waitcnt lgkmcnt(6)
	v_mfma_f32_32x32x16_bf16 v[16:31], v[220:223], v[36:39], v[16:31]
	v_mfma_f32_32x32x16_bf16 v[0:15], v[220:223], v[68:71], v[0:15]
	s_waitcnt lgkmcnt(5)
	v_mfma_f32_32x32x16_bf16 v[16:31], v[224:227], v[40:43], v[16:31]
	v_mfma_f32_32x32x16_bf16 v[0:15], v[224:227], v[72:75], v[0:15]
	s_waitcnt lgkmcnt(4)
	v_mfma_f32_32x32x16_bf16 v[16:31], v[228:231], v[44:47], v[16:31]
	v_mfma_f32_32x32x16_bf16 v[0:15], v[228:231], v[76:79], v[0:15]
	s_waitcnt lgkmcnt(3)
	v_mfma_f32_32x32x16_bf16 v[16:31], v[232:235], v[48:51], v[16:31]
	v_mfma_f32_32x32x16_bf16 v[0:15], v[232:235], v[80:83], v[0:15]
	s_waitcnt lgkmcnt(2)
	v_mfma_f32_32x32x16_bf16 v[16:31], v[236:239], v[52:55], v[16:31]
	v_mfma_f32_32x32x16_bf16 v[0:15], v[236:239], v[84:87], v[0:15]
	s_waitcnt lgkmcnt(1)
	v_mfma_f32_32x32x16_bf16 v[16:31], v[240:243], v[56:59], v[16:31]
	v_mfma_f32_32x32x16_bf16 v[0:15], v[240:243], v[88:91], v[0:15]
	s_waitcnt lgkmcnt(0)
	v_mfma_f32_32x32x16_bf16 v[16:31], v[244:247], v[60:63], v[16:31]
	v_mfma_f32_32x32x16_bf16 v[0:15], v[244:247], v[92:95], v[0:15]
	s_setprio 2
	s_nop 9
	v_fmamk_f32 v16, v16, 0xbfb8aa3b, v100
	v_exp_f32_e32 v16, v16
	v_fmamk_f32 v0, v0, 0xbfb8aa3b, v101
	v_exp_f32_e32 v0, v0
	v_fmamk_f32 v17, v17, 0xbfb8aa3b, v100
	v_add_f32_e32 v16, 1.0, v16
	v_rcp_f32_e32 v16, v16
	v_exp_f32_e32 v17, v17
	v_lshlrev_b32_e32 v105, 1, v108
	v_cmp_gt_u32_e32 vcc, 32, v108
	v_mul_f32_e32 v16, v99, v16
	v_exp_f32_e32 v16, v16
	v_lshlrev_b32_e32 v106, 4, v109
	v_mov_b32_e32 v108, s88
	s_movk_i32 s25, 0x50
	v_fma_f32 v116, -v16, v16, 1.0
	v_bitop3_b32 v113, v106, s25, v108 bitop3:0x36
	s_movk_i32 s25, 0x60
	v_add_f32_e32 v0, 1.0, v0
	v_sqrt_f32_e32 v116, v116
	v_bitop3_b32 v114, v106, s25, v108 bitop3:0x36
	s_movk_i32 s25, 0x70
	v_rcp_f32_e32 v0, v0
	v_add_f32_e32 v17, 1.0, v17
	v_fmamk_f32 v1, v1, 0xbfb8aa3b, v101
	v_fmamk_f32 v18, v18, 0xbfb8aa3b, v100
	v_lshl_add_u32 v104, v103, 12, s21
	v_and_b32_e32 v105, 14, v105
	v_or_b32_e32 v107, s88, v106
	v_bitop3_b32 v109, v106, 16, s88 bitop3:0x36
	v_bitop3_b32 v110, v106, 32, s88 bitop3:0x36
	v_bitop3_b32 v111, v106, 48, s88 bitop3:0x36
	v_bitop3_b32 v112, v106, 64, s88 bitop3:0x36
	v_bitop3_b32 v115, v106, s25, v108 bitop3:0x36
	s_and_b64 s[4:5], s[22:23], s[4:5]
	v_exp_f32_e32 v1, v1
	v_rcp_f32_e32 v117, v17
	v_exp_f32_e32 v18, v18
	v_add3_u32 v107, v104, v107, v105
	v_add3_u32 v109, v104, v109, v105
	v_add3_u32 v110, v104, v110, v105
	v_add3_u32 v111, v104, v111, v105
	v_add3_u32 v112, v104, v112, v105
	v_add3_u32 v113, v104, v113, v105
	v_add3_u32 v114, v104, v114, v105
	v_add3_u32 v115, v104, v115, v105
	s_and_b64 s[4:5], s[4:5], vcc
	ds_read_u16 v107, v107 offset:24576
	ds_read_u16 v109, v109 offset:24832
	ds_read_u16 v110, v110 offset:25088
	ds_read_u16 v111, v111 offset:25344
	ds_read_u16 v112, v112 offset:25600
	ds_read_u16 v113, v113 offset:25856
	ds_read_u16 v114, v114 offset:26112
	ds_read_u16 v115, v115 offset:26368
	v_cndmask_b32_e64 v116, v116, 1.0, s[4:5]
	s_waitcnt lgkmcnt(0)
	v_lshlrev_b32_e32 v107, 16, v107
	v_mul_f32_e32 v0, v0, v116
	v_mul_f32_e32 v17, v0, v107
	v_add_f32_e32 v0, 1.0, v1
	v_mul_f32_e32 v1, v99, v117
	v_add_f32_e32 v18, 1.0, v18
	v_fmamk_f32 v19, v19, 0xbfb8aa3b, v100
	v_exp_f32_e32 v1, v1
	v_rcp_f32_e32 v18, v18
	v_exp_f32_e32 v19, v19
	v_fmamk_f32 v2, v2, 0xbfb8aa3b, v101
	v_fma_f32 v107, -v1, v1, 1.0
	v_mul_f32_e32 v18, v99, v18
	v_add_f32_e32 v19, 1.0, v19
	v_fmamk_f32 v20, v20, 0xbfb8aa3b, v100
	v_rcp_f32_e32 v0, v0
	v_sqrt_f32_e32 v107, v107
	v_exp_f32_e32 v2, v2
	v_exp_f32_e32 v18, v18
	v_rcp_f32_e32 v19, v19
	v_exp_f32_e32 v20, v20
	v_mul_f32_e32 v0, v0, v107
	v_add_f32_e32 v2, 1.0, v2
	v_fma_f32 v107, -v18, v18, 1.0
	v_fmamk_f32 v3, v3, 0xbfb8aa3b, v101
	v_mul_f32_e32 v19, v99, v19
	v_add_f32_e32 v20, 1.0, v20
	v_fmamk_f32 v21, v21, 0xbfb8aa3b, v100
	v_rcp_f32_e32 v2, v2
	v_sqrt_f32_e32 v107, v107
	v_exp_f32_e32 v3, v3
	v_exp_f32_e32 v19, v19
	v_rcp_f32_e32 v20, v20
	v_exp_f32_e32 v21, v21
	v_mul_f32_e32 v2, v2, v107
	v_add_f32_e32 v3, 1.0, v3
	v_fma_f32 v107, -v19, v19, 1.0
	v_fmamk_f32 v4, v4, 0xbfb8aa3b, v101
	v_mul_f32_e32 v20, v99, v20
	v_add_f32_e32 v21, 1.0, v21
	v_fmamk_f32 v22, v22, 0xbfb8aa3b, v100
	v_rcp_f32_e32 v3, v3
	v_sqrt_f32_e32 v107, v107
	v_exp_f32_e32 v4, v4
	v_exp_f32_e32 v20, v20
	v_rcp_f32_e32 v21, v21
	v_exp_f32_e32 v22, v22
	v_fmamk_f32 v23, v23, 0xbfb8aa3b, v100
	v_exp_f32_e32 v23, v23
	v_mul_f32_e32 v3, v3, v107
	v_add_f32_e32 v4, 1.0, v4
	v_fma_f32 v107, -v20, v20, 1.0
	v_fmamk_f32 v5, v5, 0xbfb8aa3b, v101
	v_mul_f32_e32 v21, v99, v21
	v_add_f32_e32 v22, 1.0, v22
	v_rcp_f32_e32 v4, v4
	v_sqrt_f32_e32 v107, v107
	v_exp_f32_e32 v5, v5
	v_exp_f32_e32 v21, v21
	v_rcp_f32_e32 v22, v22
	v_add_f32_e32 v23, 1.0, v23
	v_rcp_f32_e32 v23, v23
	v_mul_f32_e32 v4, v4, v107
	v_lshlrev_b32_e32 v107, 16, v113
	v_add_f32_e32 v5, 1.0, v5
	v_fma_f32 v113, -v21, v21, 1.0
	v_fmamk_f32 v6, v6, 0xbfb8aa3b, v101
	v_mul_f32_e32 v22, v99, v22
	v_rcp_f32_e32 v5, v5
	v_sqrt_f32_e32 v113, v113
	v_exp_f32_e32 v6, v6
	v_exp_f32_e32 v22, v22
	v_fmamk_f32 v7, v7, 0xbfb8aa3b, v101
	v_mul_f32_e32 v23, v99, v23
	v_exp_f32_e32 v7, v7
	v_exp_f32_e32 v23, v23
	v_fmamk_f32 v24, v24, 0xbfb8aa3b, v100
	v_mul_f32_e32 v5, v5, v113
	v_add_f32_e32 v6, 1.0, v6
	v_fma_f32 v113, -v22, v22, 1.0
	v_exp_f32_e32 v24, v24
	v_rcp_f32_e32 v6, v6
	v_sqrt_f32_e32 v113, v113
	v_add_f32_e32 v7, 1.0, v7
	v_fma_f32 v116, -v23, v23, 1.0
	v_rcp_f32_e32 v7, v7
	v_sqrt_f32_e32 v116, v116
	s_movk_i32 s4, 0x80
	v_add_f32_e32 v24, 1.0, v24
	v_mul_f32_e32 v6, v6, v113
	v_lshlrev_b32_e32 v113, 16, v115
	v_bitop3_b32 v115, v106, s4, v108 bitop3:0x36
	s_movk_i32 s4, 0x90
	v_rcp_f32_e32 v24, v24
	v_mul_f32_e32 v7, v7, v116
	v_bitop3_b32 v116, v106, s4, v108 bitop3:0x36
	s_movk_i32 s4, 0xa0
	v_bitop3_b32 v117, v106, s4, v108 bitop3:0x36
	s_movk_i32 s4, 0xb0
	v_bitop3_b32 v118, v106, s4, v108 bitop3:0x36
	s_movk_i32 s4, 0xc0
	v_fmamk_f32 v8, v8, 0xbfb8aa3b, v101
	v_bitop3_b32 v119, v106, s4, v108 bitop3:0x36
	s_movk_i32 s4, 0xd0
	v_mul_f32_e32 v24, v99, v24
	v_exp_f32_e32 v8, v8
	v_bitop3_b32 v120, v106, s4, v108 bitop3:0x36
	s_movk_i32 s4, 0xe0
	v_fmamk_f32 v25, v25, 0xbfb8aa3b, v100
	v_exp_f32_e32 v24, v24
	v_bitop3_b32 v121, v106, s4, v108 bitop3:0x36
	s_movk_i32 s4, 0xf0
	v_exp_f32_e32 v25, v25
	v_bitop3_b32 v106, v106, s4, v108 bitop3:0x36
	v_add3_u32 v115, v104, v115, v105
	v_add3_u32 v116, v104, v116, v105
	v_add3_u32 v117, v104, v117, v105
	v_add3_u32 v118, v104, v118, v105
	v_add3_u32 v119, v104, v119, v105
	v_add3_u32 v120, v104, v120, v105
	v_add3_u32 v121, v104, v121, v105
	v_add3_u32 v104, v104, v106, v105
	ds_read_u16 v105, v115 offset:26624
	ds_read_u16 v106, v116 offset:26880
	ds_read_u16 v108, v117 offset:27136
	ds_read_u16 v115, v118 offset:27392
	ds_read_u16 v116, v119 offset:27648
	ds_read_u16 v117, v120 offset:27904
	ds_read_u16 v118, v121 offset:28160
	ds_read_u16 v104, v104 offset:28416
	v_add_f32_e32 v8, 1.0, v8
	v_fma_f32 v119, -v24, v24, 1.0
	v_fmamk_f32 v26, v26, 0xbfb8aa3b, v100
	v_rcp_f32_e32 v8, v8
	v_add_f32_e32 v25, 1.0, v25
	v_sqrt_f32_e32 v119, v119
	v_exp_f32_e32 v26, v26
	v_rcp_f32_e32 v25, v25
	v_fmamk_f32 v9, v9, 0xbfb8aa3b, v101
	v_mul_f32_e32 v119, v8, v119
	v_add_f32_e32 v8, 1.0, v26
	v_mul_f32_e32 v25, v99, v25
	v_rcp_f32_e32 v8, v8
	v_exp_f32_e32 v9, v9
	v_exp_f32_e32 v25, v25
	s_waitcnt lgkmcnt(0)
	v_lshlrev_b32_e32 v26, 16, v108
	v_mul_f32_e32 v8, v99, v8
	v_add_f32_e32 v9, 1.0, v9
	v_fma_f32 v120, -v25, v25, 1.0
	v_exp_f32_e32 v108, v8
	v_fmamk_f32 v8, v27, 0xbfb8aa3b, v100
	v_rcp_f32_e32 v9, v9
	v_sqrt_f32_e32 v120, v120
	v_exp_f32_e32 v8, v8
	v_fmamk_f32 v11, v11, 0xbfb8aa3b, v101
	v_exp_f32_e32 v11, v11
	v_mul_f32_e32 v120, v9, v120
	v_fmamk_f32 v9, v10, 0xbfb8aa3b, v101
	v_add_f32_e32 v8, 1.0, v8
	v_exp_f32_e32 v9, v9
	v_rcp_f32_e32 v8, v8
	v_fma_f32 v10, -v108, v108, 1.0
	v_sqrt_f32_e32 v10, v10
	v_add_f32_e32 v9, 1.0, v9
	v_mul_f32_e32 v8, v99, v8
	v_rcp_f32_e32 v9, v9
	v_exp_f32_e32 v27, v8
	v_add_f32_e32 v8, 1.0, v11
	v_rcp_f32_e32 v8, v8
	v_mul_f32_e32 v121, v9, v10
	v_fma_f32 v9, -v27, v27, 1.0
	v_fmamk_f32 v10, v28, 0xbfb8aa3b, v100
	v_sqrt_f32_e32 v9, v9
	v_exp_f32_e32 v10, v10
	v_fmamk_f32 v11, v13, 0xbfb8aa3b, v101
	v_exp_f32_e32 v11, v11
	v_mul_f32_e32 v28, v8, v9
	v_add_f32_e32 v9, 1.0, v10
	v_fmamk_f32 v10, v29, 0xbfb8aa3b, v100
	v_exp_f32_e32 v10, v10
	v_fmamk_f32 v8, v12, 0xbfb8aa3b, v101
	v_fmamk_f32 v13, v14, 0xbfb8aa3b, v101
	v_exp_f32_e32 v13, v13
	v_add_f32_e32 v10, 1.0, v10
	v_rcp_f32_e32 v12, v10
	v_add_f32_e32 v10, 1.0, v11
	v_fmamk_f32 v15, v15, 0xbfb8aa3b, v101
	v_exp_f32_e32 v15, v15
	v_mul_f32_e32 v11, v99, v12
	v_fmamk_f32 v12, v30, 0xbfb8aa3b, v100
	v_exp_f32_e32 v12, v12
	v_lshlrev_b32_e32 v109, 16, v109
	v_lshlrev_b32_e32 v110, 16, v110
	v_lshlrev_b32_e32 v29, 16, v117
	v_add_f32_e32 v12, 1.0, v12
	v_rcp_f32_e32 v14, v12
	v_add_f32_e32 v12, 1.0, v13
	v_lshlrev_b32_e32 v111, 16, v111
	v_lshlrev_b32_e32 v112, 16, v112
	v_mul_f32_e32 v13, v99, v14
	v_fmamk_f32 v14, v31, 0xbfb8aa3b, v100
	v_exp_f32_e32 v14, v14
	v_rcp_f32_e32 v9, v9
	v_lshlrev_b32_e32 v114, 16, v114
	v_exp_f32_e32 v8, v8
	v_add_f32_e32 v14, 1.0, v14
	v_rcp_f32_e32 v31, v14
	v_add_f32_e32 v14, 1.0, v15
	v_mul_f32_e32 v9, v99, v9
	v_exp_f32_e32 v9, v9
	v_mul_f32_e32 v15, v99, v31
	v_mul_f32_e32 v31, v1, v17
	v_fmac_f32_e32 v31, v0, v109
	v_mul_f32_e32 v117, v18, v31
	v_fmac_f32_e32 v117, v2, v110
	v_mul_f32_e32 v110, v19, v117
	v_fmac_f32_e32 v110, v3, v111
	v_mul_f32_e32 v111, v20, v110
	v_fmac_f32_e32 v111, v4, v112
	v_mul_f32_e32 v112, v21, v111
	v_fmac_f32_e32 v112, v5, v107
	v_mul_f32_e32 v107, v22, v112
	v_fmac_f32_e32 v107, v6, v114
	v_mul_f32_e32 v114, v23, v107
	v_fmac_f32_e32 v114, v7, v113
	v_lshlrev_b32_e32 v105, 16, v105
	v_mul_f32_e32 v113, v24, v114
	v_fmac_f32_e32 v113, v119, v105
	v_lshlrev_b32_e32 v106, 16, v106
	v_mul_f32_e32 v105, v25, v113
	v_add_f32_e32 v8, 1.0, v8
	v_fmac_f32_e32 v105, v120, v106
	v_fma_f32 v0, -v9, v9, 1.0
	v_rcp_f32_e32 v8, v8
	v_exp_f32_e32 v11, v11
	v_mul_f32_e32 v106, v108, v105
	v_sqrt_f32_e32 v6, v0
	v_fmac_f32_e32 v106, v121, v26
	v_lshlrev_b32_e32 v115, 16, v115
	v_mul_f32_e32 v7, v27, v106
	v_fmac_f32_e32 v7, v28, v115
	v_lshlrev_b32_e32 v116, 16, v116
	v_pk_mul_f32 v[2:3], v[8:9], v[6:7]
	v_fma_f32 v0, -v11, v11, 1.0
	v_rcp_f32_e32 v10, v10
	v_fmac_f32_e32 v3, v2, v116
	v_sqrt_f32_e32 v2, v0
	v_exp_f32_e32 v13, v13
	v_mul_f32_e32 v109, v1, v16
	v_mul_f32_e32 v18, v18, v109
	v_mul_f32_e32 v19, v19, v18
	v_mul_f32_e32 v20, v20, v19
	v_pk_mul_f32 v[0:1], v[10:11], v[2:3]
	v_mul_f32_e32 v21, v21, v20
	v_fmac_f32_e32 v1, v0, v29
	v_fma_f32 v0, -v13, v13, 1.0
	v_rcp_f32_e32 v12, v12
	v_exp_f32_e32 v15, v15
	v_mul_f32_e32 v6, v22, v21
	v_sqrt_f32_e32 v0, v0
	v_mul_f32_e32 v22, v23, v6
	v_mul_f32_e32 v23, v24, v22
	v_mul_f32_e32 v2, v25, v23
	v_lshlrev_b32_e32 v30, 16, v118
	v_mul_f32_e32 v10, v108, v2
	v_pk_mul_f32 v[4:5], v[12:13], v[0:1]
	v_fma_f32 v0, -v15, v15, 1.0
	v_rcp_f32_e32 v14, v14
	v_mul_f32_e32 v24, v27, v10
	v_fmac_f32_e32 v5, v4, v30
	v_sqrt_f32_e32 v4, v0
	v_mul_f32_e32 v0, v9, v24
	v_mul_f32_e32 v11, v11, v0
	v_mul_f32_e32 v12, v13, v11
	v_pk_mul_f32 v[8:9], v[14:15], v[4:5]
	v_mul_f32_e32 v4, v15, v12
	s_add_i32 s21, s21, s78
	v_lshlrev_b32_e32 v14, 10, v103
	v_lshlrev_b32_e32 v15, 1, v102
	v_lshlrev_b32_e32 v104, 16, v104
	v_add3_u32 v14, s21, v14, v15
	v_fmac_f32_e32 v9, v8, v104
	v_or_b32_e32 v13, v102, v184
	ds_read_u16 v15, v14 offset:49152
	ds_read_u16 v25, v14 offset:49216
	ds_read_u16 v26, v14 offset:49280
	ds_read_u16 v27, v14 offset:49344
	ds_read_u16 v28, v14 offset:49408
	ds_read_u16 v29, v14 offset:49472
	ds_read_u16 v30, v14 offset:49536
	ds_read_u16 v102, v14 offset:49600
	v_fma_f32 v8, v98, v4, v9
	v_lshlrev_b32_e32 v13, 2, v13
	s_waitcnt lgkmcnt(7)
	v_lshlrev_b32_e32 v15, 16, v15
	ds_bpermute_b32 v8, v13, v8
	v_mul_f32_e32 v103, 0xbfb8aa3b, v15
	v_exp_f32_e32 v103, v103
	s_add_i32 s7, s7, 32
	s_cmp_eq_u32 s55, s20
	s_waitcnt lgkmcnt(0)
	v_cndmask_b32_e32 v8, v8, v98, vcc
	v_add_f32_e32 v98, 1.0, v103
	v_rcp_f32_e32 v103, v98
	v_fmac_f32_e32 v9, v8, v4
	ds_bpermute_b32 v98, v13, v9 offset:128
	v_lshlrev_b32_e32 v13, 16, v25
	v_mul_f32_e32 v4, v103, v15
	v_mul_f32_e32 v15, 0xbfb8aa3b, v13
	v_exp_f32_e32 v15, v15
	v_fmac_f32_e32 v17, v16, v8
	v_mul_f32_e32 v4, v17, v4
	v_cvt_pk_bf16_f32 v4, v4, s0
	ds_write_b16 v14, v4 offset:49152
	v_add_f32_e32 v4, 1.0, v15
	v_lshlrev_b32_e32 v15, 16, v26
	v_mul_f32_e32 v16, 0xbfb8aa3b, v15
	v_rcp_f32_e32 v4, v4
	v_exp_f32_e32 v16, v16
	v_fmac_f32_e32 v31, v109, v8
	v_fmac_f32_e32 v117, v18, v8
	v_mul_f32_e32 v4, v4, v13
	v_add_f32_e32 v13, 1.0, v16
	v_rcp_f32_e32 v13, v13
	v_mul_f32_e32 v4, v31, v4
	v_cvt_pk_bf16_f32 v4, v4, s0
	ds_write_b16 v14, v4 offset:49216
	v_mul_f32_e32 v4, v13, v15
	v_lshlrev_b32_e32 v13, 16, v27
	v_mul_f32_e32 v15, 0xbfb8aa3b, v13
	v_exp_f32_e32 v15, v15
	v_mul_f32_e32 v4, v117, v4
	v_cvt_pk_bf16_f32 v4, v4, s0
	ds_write_b16 v14, v4 offset:49280
	v_add_f32_e32 v4, 1.0, v15
	v_lshlrev_b32_e32 v15, 16, v28
	v_mul_f32_e32 v16, 0xbfb8aa3b, v15
	v_rcp_f32_e32 v4, v4
	v_exp_f32_e32 v16, v16
	v_fmac_f32_e32 v110, v19, v8
	v_fmac_f32_e32 v111, v20, v8
	v_mul_f32_e32 v4, v4, v13
	v_add_f32_e32 v13, 1.0, v16
	v_rcp_f32_e32 v13, v13
	v_mul_f32_e32 v4, v110, v4
	v_cvt_pk_bf16_f32 v4, v4, s0
	ds_write_b16 v14, v4 offset:49344
	v_mul_f32_e32 v4, v13, v15
	v_lshlrev_b32_e32 v13, 16, v29
	v_mul_f32_e32 v15, 0xbfb8aa3b, v13
	v_exp_f32_e32 v15, v15
	v_mul_f32_e32 v4, v111, v4
	v_cvt_pk_bf16_f32 v4, v4, s0
	ds_write_b16 v14, v4 offset:49408
	v_add_f32_e32 v4, 1.0, v15
	v_lshlrev_b32_e32 v15, 16, v30
	v_mul_f32_e32 v16, 0xbfb8aa3b, v15
	v_rcp_f32_e32 v4, v4
	v_exp_f32_e32 v16, v16
	v_fmac_f32_e32 v112, v21, v8
	v_fmac_f32_e32 v107, v6, v8
	v_mul_f32_e32 v4, v4, v13
	v_add_f32_e32 v13, 1.0, v16
	v_rcp_f32_e32 v13, v13
	v_mul_f32_e32 v4, v112, v4
	v_cvt_pk_bf16_f32 v4, v4, s0
	v_lshlrev_b32_e32 v6, 16, v102
	ds_write_b16 v14, v4 offset:49472
	v_mul_f32_e32 v4, v13, v15
	v_mul_f32_e32 v13, 0xbfb8aa3b, v6
	v_exp_f32_e32 v13, v13
	v_mul_f32_e32 v4, v107, v4
	v_cvt_pk_bf16_f32 v4, v4, s0
	ds_write_b16 v14, v4 offset:49536
	v_add_f32_e32 v4, 1.0, v13
	ds_read_u16 v13, v14 offset:49664
	ds_read_u16 v15, v14 offset:49728
	ds_read_u16 v16, v14 offset:49792
	ds_read_u16 v17, v14 offset:49856
	ds_read_u16 v18, v14 offset:49920
	ds_read_u16 v19, v14 offset:49984
	ds_read_u16 v20, v14 offset:50048
	ds_read_u16 v21, v14 offset:50112
	s_waitcnt lgkmcnt(7)
	v_lshlrev_b32_e32 v13, 16, v13
	v_mul_f32_e32 v25, 0xbfb8aa3b, v13
	v_rcp_f32_e32 v4, v4
	v_exp_f32_e32 v25, v25
	v_fmac_f32_e32 v114, v22, v8
	v_fmac_f32_e32 v113, v23, v8
	v_mul_f32_e32 v4, v4, v6
	v_add_f32_e32 v6, 1.0, v25
	v_rcp_f32_e32 v6, v6
	v_mul_f32_e32 v4, v114, v4
	v_cvt_pk_bf16_f32 v4, v4, s0
	ds_write_b16 v14, v4 offset:49600
	v_mul_f32_e32 v4, v6, v13
	s_waitcnt lgkmcnt(7)
	v_lshlrev_b32_e32 v6, 16, v15
	v_mul_f32_e32 v13, 0xbfb8aa3b, v6
	v_exp_f32_e32 v13, v13
	v_mul_f32_e32 v4, v113, v4
	v_cvt_pk_bf16_f32 v4, v4, s0
	ds_write_b16 v14, v4 offset:49664
	v_add_f32_e32 v4, 1.0, v13
	s_waitcnt lgkmcnt(7)
	v_lshlrev_b32_e32 v13, 16, v16
	v_mul_f32_e32 v15, 0xbfb8aa3b, v13
	v_rcp_f32_e32 v4, v4
	v_exp_f32_e32 v15, v15
	v_fmac_f32_e32 v105, v2, v8
	v_fmac_f32_e32 v106, v10, v8
	v_mul_f32_e32 v2, v4, v6
	v_add_f32_e32 v4, 1.0, v15
	v_rcp_f32_e32 v4, v4
	v_mul_f32_e32 v2, v105, v2
	v_cvt_pk_bf16_f32 v2, v2, s0
	ds_write_b16 v14, v2 offset:49728
	v_mul_f32_e32 v2, v4, v13
	s_waitcnt lgkmcnt(7)
	v_lshlrev_b32_e32 v4, 16, v17
	v_mul_f32_e32 v6, 0xbfb8aa3b, v4
	v_exp_f32_e32 v6, v6
	v_mul_f32_e32 v2, v106, v2
	v_cvt_pk_bf16_f32 v2, v2, s0
	ds_write_b16 v14, v2 offset:49792
	v_add_f32_e32 v2, 1.0, v6
	s_waitcnt lgkmcnt(7)
	v_lshlrev_b32_e32 v6, 16, v18
	v_mul_f32_e32 v10, 0xbfb8aa3b, v6
	v_rcp_f32_e32 v2, v2
	v_exp_f32_e32 v10, v10
	v_fmac_f32_e32 v7, v24, v8
	v_fmac_f32_e32 v3, v0, v8
	v_mul_f32_e32 v2, v2, v4
	v_add_f32_e32 v4, 1.0, v10
	v_rcp_f32_e32 v4, v4
	v_mul_f32_e32 v2, v7, v2
	v_cvt_pk_bf16_f32 v2, v2, s0
	ds_write_b16 v14, v2 offset:49856
	v_mul_f32_e32 v0, v4, v6
	s_waitcnt lgkmcnt(7)
	v_lshlrev_b32_e32 v2, 16, v19
	v_mul_f32_e32 v0, v3, v0
	v_mul_f32_e32 v3, 0xbfb8aa3b, v2
	v_exp_f32_e32 v3, v3
	v_cvt_pk_bf16_f32 v0, v0, s0
	ds_write_b16 v14, v0 offset:49920
	v_fmac_f32_e32 v1, v8, v11
	v_add_f32_e32 v0, 1.0, v3
	s_waitcnt lgkmcnt(7)
	v_lshlrev_b32_e32 v3, 16, v20
	v_rcp_f32_e32 v0, v0
	v_mul_f32_e32 v4, 0xbfb8aa3b, v3
	v_exp_f32_e32 v4, v4
	v_fmac_f32_e32 v5, v8, v12
	v_mul_f32_e32 v0, v0, v2
	s_waitcnt lgkmcnt(6)
	v_lshlrev_b32_e32 v2, 16, v21
	v_mul_f32_e32 v0, v1, v0
	v_add_f32_e32 v1, 1.0, v4
	v_mul_f32_e32 v4, 0xbfb8aa3b, v2
	v_rcp_f32_e32 v1, v1
	v_exp_f32_e32 v4, v4
	v_cvt_pk_bf16_f32 v0, v0, s0
	ds_write_b16 v14, v0 offset:49984
	v_mul_f32_e32 v0, v1, v3
	v_add_f32_e32 v1, 1.0, v4
	v_rcp_f32_e32 v1, v1
	v_mul_f32_e32 v0, v5, v0
	v_cvt_pk_bf16_f32 v0, v0, s0
	ds_write_b16 v14, v0 offset:50048
	v_mul_f32_e32 v0, v1, v2
	v_mul_f32_e32 v0, v9, v0
	v_cvt_pk_bf16_f32 v0, v0, s0
	ds_write_b16 v14, v0 offset:50112
	s_waitcnt vmcnt(0) lgkmcnt(0)
	s_barrier
	s_cbranch_scc1 .LBB0_589
	s_mov_b32 s21, s20
	s_cmp_eq_u32 s21, 0
	s_cselect_b64 s[4:5], -1, 0
	s_and_b64 vcc, exec, s[4:5]
	s_cbranch_vccz .LBB0_584
	s_branch .LBB0_585
.LBB0_589:
	s_setprio 0
	v_mov_b32_e32 v0, v182
	s_add_i32 s28, s28, s94
	v_lshrrev_b32_e32 v1, 2, v0
	v_lshl_add_u32 v8, v0, 4, s9
	v_lshlrev_b32_e32 v0, 3, v0
	v_add_u32_e32 v5, s28, v1
	v_and_or_b32 v4, v0, 24, s6
	ds_read_b128 v[0:3], v8 offset:49152
	v_mad_u64_u32 v[4:5], s[4:5], v5, s91, v[4:5]
	v_mov_b32_e32 v5, v153
	v_lshl_add_u64 v[6:7], v[4:5], 1, s[26:27]
	s_waitcnt lgkmcnt(0)
	global_store_dwordx4 v[6:7], v[0:3], off
	ds_read_b128 v[0:3], v8 offset:50176
	v_add_u32_e32 v152, 0x12000, v4
	v_lshl_add_u64 v[4:5], v[152:153], 1, s[26:27]
	s_waitcnt lgkmcnt(0)
	global_store_dwordx4 v[4:5], v[0:3], off
	s_waitcnt lgkmcnt(0)
	s_and_saveexec_b64 s[4:5], s[0:1]
	s_cbranch_execz .LBB0_530
	s_ashr_i32 s25, s24, 31
	s_lshl_b64 s[6:7], s[24:25], 12
	s_add_u32 s6, s87, s6
	v_readlane_b32 s12, v255, 9
	s_addc_u32 s7, s12, s7
	v_lshl_add_u64 v[0:1], v[96:97], 2, s[6:7]
	global_store_dword v[0:1], v98, off
	s_branch .LBB0_530

.LBB0_620:
	v_add_co_u32_e32 v24, vcc, s99, v18
	s_movk_i32 s1, 0x1000
	s_nop 0
	v_addc_co_u32_e32 v25, vcc, 0, v19, vcc
	v_add_co_u32_e32 v94, vcc, s1, v18
	s_movk_i32 s3, 0x2000
	s_nop 0
	v_addc_co_u32_e32 v95, vcc, 0, v19, vcc
	v_add_co_u32_e32 v26, vcc, s3, v18
	v_lshl_add_u64 v[22:23], s[28:29], 0, v[20:21]
	s_add_u32 s0, s28, s66
	s_mov_b32 s5, 0x100000
	v_addc_co_u32_e32 v27, vcc, 0, v19, vcc
	s_mov_b32 s4, 0x358637bd
	s_addc_u32 s1, s29, s67
	v_add_co_u32_e32 v44, vcc, s5, v22
	s_mov_b32 s6, 0x101000
	v_mov_b64_e32 v[92:93], s[4:5]
	s_add_u32 s4, s0, 0x3c1d8000
	v_addc_co_u32_e32 v45, vcc, 0, v23, vcc
	v_add_co_u32_e32 v22, vcc, s6, v22
	s_addc_u32 s5, s1, 0
	global_load_dwordx4 v[28:31], v220, s[0:1]
	global_load_dwordx4 v[32:35], v220, s[0:1] offset:64
	global_load_dwordx4 v[36:39], v220, s[0:1] offset:128
	global_load_dwordx4 v[40:43], v220, s[0:1] offset:192
	global_load_dwordx2 v[96:97], v[44:45], off offset:512
	global_load_dwordx2 v[98:99], v[44:45], off offset:1024
	global_load_dwordx2 v[100:101], v[44:45], off offset:1536
	global_load_dwordx2 v[102:103], v[44:45], off offset:2048
	global_load_dwordx2 v[104:105], v[44:45], off offset:2560
	global_load_dwordx2 v[106:107], v[44:45], off offset:3072
	global_load_dwordx2 v[108:109], v[44:45], off offset:3584
	v_addc_co_u32_e32 v23, vcc, 0, v23, vcc
	global_load_dwordx4 v[44:47], v0, s[4:5] offset:16
	global_load_dwordx4 v[48:51], v0, s[4:5] offset:32
	global_load_dwordx4 v[52:55], v0, s[4:5] offset:48
	global_load_dwordx2 v[110:111], v[22:23], off offset:-4096
	global_load_dwordx2 v[112:113], v[22:23], off
	global_load_dwordx2 v[114:115], v[22:23], off offset:512
	global_load_dwordx2 v[116:117], v[22:23], off offset:1024
	global_load_dwordx2 v[118:119], v[22:23], off offset:1536
	global_load_dwordx2 v[120:121], v[22:23], off offset:2048
	global_load_dwordx2 v[122:123], v[22:23], off offset:2560
	s_add_u32 s4, s0, 0x3c1d8040
	s_addc_u32 s5, s1, 0
	global_load_dwordx2 v[124:125], v[22:23], off offset:3072
	s_nop 0
	global_load_dwordx2 v[22:23], v[22:23], off offset:3584
	s_nop 0
	global_load_dwordx4 v[56:59], v0, s[4:5] offset:32
	global_load_dwordx4 v[60:63], v0, s[4:5] offset:48
	global_load_dwordx4 v[64:67], v0, s[4:5] offset:16
	s_add_u32 s4, s0, 0x3c1d8080
	s_addc_u32 s5, s1, 0
	global_load_dwordx4 v[68:71], v0, s[4:5] offset:48
	global_load_dwordx4 v[72:75], v0, s[4:5] offset:32
	global_load_dwordx4 v[76:79], v0, s[4:5] offset:16
	s_add_u32 s0, s0, 0x3c1d80c0
	s_addc_u32 s1, s1, 0
	global_load_dwordx4 v[80:83], v0, s[0:1] offset:32
	global_load_dwordx4 v[84:87], v0, s[0:1] offset:48
	global_load_dwordx4 v[88:91], v0, s[0:1] offset:16
	s_add_i32 s58, s58, s60
	s_add_u32 s66, s66, s68
	s_addc_u32 s67, s67, s69
	v_lshl_add_u64 v[20:21], v[20:21], 0, s[64:65]
	s_cmpk_lt_i32 s58, 0x4000
	s_waitcnt vmcnt(0)
	v_pk_add_f32 v[30:31], v[30:31], v[46:47]
	v_pk_add_f32 v[28:29], v[28:29], v[44:45]
	s_waitcnt vmcnt(18)
	v_pk_add_f32 v[44:45], v[50:51], v[54:55]
	v_pk_add_f32 v[46:47], v[48:49], v[52:53]
	v_pk_add_f32 v[30:31], v[30:31], v[44:45]
	v_pk_add_f32 v[28:29], v[28:29], v[46:47]
	v_mov_b32_e32 v45, v30
	v_mov_b32_e32 v44, v29
	v_mov_b32_e32 v29, v31
	v_pk_add_f32 v[28:29], v[44:45], v[28:29]
	s_waitcnt vmcnt(17)
	v_lshlrev_b32_e32 v48, 16, v110
	v_and_b32_e32 v49, 0xffff0000, v110
	s_waitcnt vmcnt(7)
	v_pk_add_f32 v[46:47], v[56:57], v[60:61]
	s_waitcnt vmcnt(6)
	v_pk_add_f32 v[30:31], v[34:35], v[66:67]
	v_pk_add_f32 v[32:33], v[32:33], v[64:65]
	v_pk_add_f32 v[34:35], v[58:59], v[62:63]
	v_pk_add_f32 v[32:33], v[32:33], v[46:47]
	v_pk_add_f32 v[30:31], v[30:31], v[34:35]
	v_mov_b32_e32 v34, v33
	v_mov_b32_e32 v35, v30
	v_mov_b32_e32 v33, v31
	s_waitcnt vmcnt(3)
	v_pk_add_f32 v[38:39], v[38:39], v[78:79]
	v_pk_add_f32 v[36:37], v[36:37], v[76:77]
	v_pk_add_f32 v[44:45], v[74:75], v[70:71]
	v_pk_add_f32 v[46:47], v[72:73], v[68:69]
	v_pk_add_f32 v[32:33], v[34:35], v[32:33]
	v_pk_add_f32 v[34:35], v[38:39], v[44:45]
	v_pk_add_f32 v[36:37], v[36:37], v[46:47]
	v_mov_b32_e32 v31, v28
	v_mov_b32_e32 v30, v32
	v_mov_b32_e32 v28, v33
	v_mov_b32_e32 v32, v37
	v_mov_b32_e32 v33, v34
	v_mov_b32_e32 v37, v35
	s_waitcnt vmcnt(0)
	v_pk_add_f32 v[34:35], v[42:43], v[90:91]
	v_pk_add_f32 v[38:39], v[40:41], v[88:89]
	v_pk_add_f32 v[40:41], v[82:83], v[86:87]
	v_pk_add_f32 v[42:43], v[80:81], v[84:85]
	v_pk_add_f32 v[28:29], v[30:31], v[28:29]
	v_pk_add_f32 v[30:31], v[32:33], v[36:37]
	v_pk_add_f32 v[32:33], v[34:35], v[40:41]
	v_pk_add_f32 v[34:35], v[38:39], v[42:43]
	v_pk_fma_f32 v[28:29], v[28:29], s[22:23], v[92:93] op_sel_hi:[1,0,0]
	v_mov_b32_e32 v36, v35
	v_mov_b32_e32 v37, v32
	v_mov_b32_e32 v35, v33
	v_mov_b32_e32 v33, v30
	v_mul_f32_e32 v30, 0x4b800000, v28
	v_cmp_gt_f32_e32 vcc, s98, v28
	v_pk_add_f32 v[34:35], v[36:37], v[34:35]
	v_mul_f32_e32 v1, 0x4b800000, v29
	v_cmp_gt_f32_e64 s[0:1], s98, v29
	v_cndmask_b32_e32 v28, v28, v30, vcc
	v_mov_b32_e32 v32, v34
	v_mov_b32_e32 v30, v35
	v_cndmask_b32_e64 v1, v29, v1, s[0:1]
	v_rsq_f32_e32 v34, v28
	v_pk_add_f32 v[28:29], v[32:33], v[30:31]
	v_rsq_f32_e32 v1, v1
	v_pk_fma_f32 v[28:29], v[28:29], s[22:23], v[92:93] op_sel_hi:[1,0,0]
	v_lshlrev_b32_e32 v50, 16, v111
	v_mul_f32_e32 v30, 0x4b800000, v29
	v_cmp_gt_f32_e64 s[6:7], s98, v29
	v_mul_f32_e32 v31, 0x4b800000, v28
	v_cmp_gt_f32_e64 s[4:5], s98, v28
	v_cndmask_b32_e64 v29, v29, v30, s[6:7]
	v_rsq_f32_e32 v64, v29
	v_cndmask_b32_e64 v28, v28, v31, s[4:5]
	v_mul_f32_e32 v30, 0x45800000, v1
	v_rsq_f32_e32 v65, v28
	v_and_b32_e32 v51, 0xffff0000, v111
	v_mul_f32_e32 v31, 0x45800000, v34
	v_cndmask_b32_e64 v28, v1, v30, s[0:1]
	v_lshlrev_b32_e32 v126, 16, v96
	v_and_b32_e32 v127, 0xffff0000, v96
	v_lshlrev_b32_e32 v96, 16, v97
	v_and_b32_e32 v97, 0xffff0000, v97
	v_lshlrev_b32_e32 v128, 16, v98
	v_and_b32_e32 v129, 0xffff0000, v98
	v_lshlrev_b32_e32 v98, 16, v99
	v_and_b32_e32 v99, 0xffff0000, v99
	v_lshlrev_b32_e32 v130, 16, v100
	v_and_b32_e32 v131, 0xffff0000, v100
	v_lshlrev_b32_e32 v100, 16, v101
	v_and_b32_e32 v101, 0xffff0000, v101
	v_lshlrev_b32_e32 v132, 16, v102
	v_and_b32_e32 v133, 0xffff0000, v102
	v_lshlrev_b32_e32 v102, 16, v103
	v_and_b32_e32 v103, 0xffff0000, v103
	v_lshlrev_b32_e32 v134, 16, v104
	v_and_b32_e32 v135, 0xffff0000, v104
	v_lshlrev_b32_e32 v104, 16, v105
	v_and_b32_e32 v105, 0xffff0000, v105
	v_lshlrev_b32_e32 v136, 16, v106
	v_and_b32_e32 v137, 0xffff0000, v106
	v_lshlrev_b32_e32 v106, 16, v107
	v_and_b32_e32 v107, 0xffff0000, v107
	v_lshlrev_b32_e32 v138, 16, v108
	v_and_b32_e32 v139, 0xffff0000, v108
	v_lshlrev_b32_e32 v108, 16, v109
	v_and_b32_e32 v109, 0xffff0000, v109
	v_cndmask_b32_e32 v30, v34, v31, vcc
	v_pk_mul_f32 v[32:33], v[28:29], v[48:49] op_sel_hi:[0,1]
	v_pk_mul_f32 v[34:35], v[28:29], v[50:51] op_sel_hi:[0,1]
	v_pk_mul_f32 v[36:37], v[28:29], v[126:127] op_sel_hi:[0,1]
	v_pk_mul_f32 v[38:39], v[28:29], v[96:97] op_sel_hi:[0,1]
	v_pk_mul_f32 v[40:41], v[28:29], v[128:129] op_sel_hi:[0,1]
	v_pk_mul_f32 v[42:43], v[28:29], v[98:99] op_sel_hi:[0,1]
	v_pk_mul_f32 v[44:45], v[28:29], v[130:131] op_sel_hi:[0,1]
	v_pk_mul_f32 v[46:47], v[28:29], v[100:101] op_sel_hi:[0,1]
	v_pk_mul_f32 v[48:49], v[30:31], v[132:133] op_sel_hi:[0,1]
	v_pk_mul_f32 v[50:51], v[30:31], v[102:103] op_sel_hi:[0,1]
	v_pk_mul_f32 v[52:53], v[30:31], v[134:135] op_sel_hi:[0,1]
	v_pk_mul_f32 v[54:55], v[30:31], v[104:105] op_sel_hi:[0,1]
	v_pk_mul_f32 v[56:57], v[30:31], v[136:137] op_sel_hi:[0,1]
	v_pk_mul_f32 v[58:59], v[30:31], v[106:107] op_sel_hi:[0,1]
	v_pk_mul_f32 v[60:61], v[30:31], v[138:139] op_sel_hi:[0,1]
	v_pk_mul_f32 v[62:63], v[30:31], v[108:109] op_sel_hi:[0,1]
	v_pk_mul_f32 v[30:31], v[4:5], v[34:35]
	v_pk_mul_f32 v[28:29], v[2:3], v[32:33]
	v_mul_f32_e32 v1, 0x45800000, v64
	v_lshlrev_b32_e32 v110, 16, v112
	v_and_b32_e32 v111, 0xffff0000, v112
	v_lshlrev_b32_e32 v112, 16, v113
	v_and_b32_e32 v113, 0xffff0000, v113
	v_pk_mul_f32 v[34:35], v[8:9], v[38:39]
	v_pk_mul_f32 v[32:33], v[6:7], v[36:37]
	v_pk_mul_f32 v[38:39], v[12:13], v[42:43]
	v_pk_mul_f32 v[36:37], v[10:11], v[40:41]
	v_pk_mul_f32 v[42:43], v[16:17], v[46:47]
	v_pk_mul_f32 v[40:41], v[14:15], v[44:45]
	v_pk_mul_f32 v[46:47], v[4:5], v[50:51]
	v_pk_mul_f32 v[44:45], v[2:3], v[48:49]
	v_pk_mul_f32 v[50:51], v[8:9], v[54:55]
	v_pk_mul_f32 v[48:49], v[6:7], v[52:53]
	v_pk_mul_f32 v[54:55], v[12:13], v[58:59]
	v_pk_mul_f32 v[52:53], v[10:11], v[56:57]
	v_pk_mul_f32 v[58:59], v[16:17], v[62:63]
	v_pk_mul_f32 v[56:57], v[14:15], v[60:61]
	global_store_dwordx4 v[18:19], v[28:31], off nt
	global_store_dwordx4 v[18:19], v[32:35], off offset:1024 nt
	global_store_dwordx4 v[18:19], v[36:39], off offset:2048 nt
	global_store_dwordx4 v[18:19], v[40:43], off offset:3072 nt
	global_store_dwordx4 v[26:27], v[44:47], off offset:-4096 nt
	global_store_dwordx4 v[94:95], v[48:51], off offset:1024 nt
	global_store_dwordx4 v[94:95], v[52:55], off offset:2048 nt
	global_store_dwordx4 v[94:95], v[56:59], off offset:3072 nt
	v_mul_f32_e32 v29, 0x45800000, v65
	v_cndmask_b32_e64 v28, v64, v1, s[6:7]
	v_lshlrev_b32_e32 v140, 16, v114
	v_and_b32_e32 v141, 0xffff0000, v114
	v_lshlrev_b32_e32 v114, 16, v115
	v_and_b32_e32 v115, 0xffff0000, v115
	v_lshlrev_b32_e32 v142, 16, v116
	v_and_b32_e32 v143, 0xffff0000, v116
	v_lshlrev_b32_e32 v116, 16, v117
	v_and_b32_e32 v117, 0xffff0000, v117
	v_lshlrev_b32_e32 v144, 16, v118
	v_and_b32_e32 v145, 0xffff0000, v118
	v_lshlrev_b32_e32 v118, 16, v119
	v_and_b32_e32 v119, 0xffff0000, v119
	v_lshlrev_b32_e32 v146, 16, v120
	v_and_b32_e32 v147, 0xffff0000, v120
	v_lshlrev_b32_e32 v120, 16, v121
	v_and_b32_e32 v121, 0xffff0000, v121
	v_lshlrev_b32_e32 v148, 16, v122
	v_and_b32_e32 v149, 0xffff0000, v122
	v_lshlrev_b32_e32 v122, 16, v123
	v_and_b32_e32 v123, 0xffff0000, v123
	v_lshlrev_b32_e32 v150, 16, v124
	v_and_b32_e32 v151, 0xffff0000, v124
	v_lshlrev_b32_e32 v124, 16, v125
	v_and_b32_e32 v125, 0xffff0000, v125
	v_lshlrev_b32_e32 v152, 16, v22
	v_and_b32_e32 v153, 0xffff0000, v22
	v_lshlrev_b32_e32 v22, 16, v23
	v_and_b32_e32 v23, 0xffff0000, v23
	v_cndmask_b32_e64 v30, v65, v29, s[4:5]
	v_pk_mul_f32 v[32:33], v[28:29], v[110:111] op_sel_hi:[0,1]
	v_pk_mul_f32 v[34:35], v[28:29], v[112:113] op_sel_hi:[0,1]
	v_lshl_add_u64 v[18:19], v[18:19], 0, s[62:63]
	v_pk_mul_f32 v[36:37], v[28:29], v[140:141] op_sel_hi:[0,1]
	v_pk_mul_f32 v[38:39], v[28:29], v[114:115] op_sel_hi:[0,1]
	v_pk_mul_f32 v[40:41], v[28:29], v[142:143] op_sel_hi:[0,1]
	v_pk_mul_f32 v[42:43], v[28:29], v[116:117] op_sel_hi:[0,1]
	v_pk_mul_f32 v[44:45], v[28:29], v[144:145] op_sel_hi:[0,1]
	v_pk_mul_f32 v[46:47], v[28:29], v[118:119] op_sel_hi:[0,1]
	v_pk_mul_f32 v[48:49], v[30:31], v[146:147] op_sel_hi:[0,1]
	v_pk_mul_f32 v[50:51], v[30:31], v[120:121] op_sel_hi:[0,1]
	v_pk_mul_f32 v[52:53], v[30:31], v[148:149] op_sel_hi:[0,1]
	v_pk_mul_f32 v[54:55], v[30:31], v[122:123] op_sel_hi:[0,1]
	v_pk_mul_f32 v[56:57], v[30:31], v[150:151] op_sel_hi:[0,1]
	v_pk_mul_f32 v[58:59], v[30:31], v[124:125] op_sel_hi:[0,1]
	v_pk_mul_f32 v[60:61], v[30:31], v[152:153] op_sel_hi:[0,1]
	v_pk_mul_f32 v[22:23], v[30:31], v[22:23] op_sel_hi:[0,1]
	v_pk_mul_f32 v[30:31], v[4:5], v[34:35]
	v_pk_mul_f32 v[28:29], v[2:3], v[32:33]
	v_pk_mul_f32 v[34:35], v[8:9], v[38:39]
	v_pk_mul_f32 v[32:33], v[6:7], v[36:37]
	v_pk_mul_f32 v[38:39], v[12:13], v[42:43]
	v_pk_mul_f32 v[36:37], v[10:11], v[40:41]
	v_pk_mul_f32 v[42:43], v[16:17], v[46:47]
	v_pk_mul_f32 v[40:41], v[14:15], v[44:45]
	v_pk_mul_f32 v[46:47], v[4:5], v[50:51]
	v_pk_mul_f32 v[44:45], v[2:3], v[48:49]
	v_pk_mul_f32 v[50:51], v[8:9], v[54:55]
	v_pk_mul_f32 v[48:49], v[6:7], v[52:53]
	v_pk_mul_f32 v[54:55], v[12:13], v[58:59]
	v_pk_mul_f32 v[52:53], v[10:11], v[56:57]
	v_pk_mul_f32 v[58:59], v[16:17], v[22:23]
	v_pk_mul_f32 v[56:57], v[14:15], v[60:61]
	global_store_dwordx4 v[26:27], v[28:31], off nt
	global_store_dwordx4 v[26:27], v[32:35], off offset:1024 nt
	global_store_dwordx4 v[26:27], v[36:39], off offset:2048 nt
	global_store_dwordx4 v[26:27], v[40:43], off offset:3072 nt
	global_store_dwordx4 v[24:25], v[44:47], off nt
	global_store_dwordx4 v[24:25], v[48:51], off offset:1024 nt
	global_store_dwordx4 v[24:25], v[52:55], off offset:2048 nt
	global_store_dwordx4 v[24:25], v[56:59], off offset:3072 nt
	s_cbranch_scc1 .LBB0_620

.LBB0_706:
	v_add_co_u32_e32 v32, vcc, s20, v18
	v_lshl_add_u64 v[38:39], s[24:25], 0, v[22:23]
	s_nop 0
	v_addc_co_u32_e32 v33, vcc, 0, v19, vcc
	v_add_co_u32_e32 v34, vcc, s21, v18
	v_lshl_add_u64 v[36:37], s[24:25], 0, v[28:29]
	s_nop 0
	v_addc_co_u32_e32 v35, vcc, 0, v19, vcc
	v_add_co_u32_e32 v40, vcc, s22, v18
	v_add_co_u32_e64 v94, s[0:1], s18, v38
	s_nop 0
	v_addc_co_u32_e32 v41, vcc, 0, v19, vcc
	v_add_co_u32_e32 v92, vcc, 0x100000, v38
	v_lshl_add_u64 v[90:91], v[36:37], 0, s[8:9]
	s_nop 0
	v_addc_co_u32_e32 v93, vcc, 0, v39, vcc
	v_add_co_u32_e32 v98, vcc, 0x3c1d8000, v36
	v_lshl_add_u64 v[86:87], v[36:37], 0, s[10:11]
	v_lshl_add_u64 v[88:89], v[36:37], 0, s[12:13]
	v_addc_co_u32_e64 v95, s[0:1], 0, v39, s[0:1]
	v_lshl_add_u64 v[96:97], v[36:37], 0, s[14:15]
	v_addc_co_u32_e32 v99, vcc, 0, v37, vcc
	global_load_dwordx4 v[42:45], v[86:87], off offset:32
	global_load_dwordx4 v[46:49], v[86:87], off offset:48
	global_load_dwordx4 v[50:53], v[88:89], off offset:32
	global_load_dwordx4 v[54:57], v[88:89], off offset:48
	global_load_dwordx2 v[102:103], v[94:95], off
	global_load_dwordx2 v[104:105], v[94:95], off offset:512
	global_load_dwordx2 v[106:107], v[94:95], off offset:1024
	global_load_dwordx2 v[108:109], v[94:95], off offset:1536
	global_load_dwordx4 v[58:61], v[96:97], off offset:32
	global_load_dwordx4 v[62:65], v[96:97], off offset:48
	global_load_dwordx2 v[110:111], v[94:95], off offset:2048
	global_load_dwordx2 v[112:113], v[94:95], off offset:2560
	global_load_dwordx2 v[114:115], v[94:95], off offset:3072
	global_load_dwordx4 v[66:69], v[90:91], off offset:32
	global_load_dwordx4 v[70:73], v[90:91], off offset:16
	global_load_dwordx4 v[74:77], v[86:87], off offset:16
	global_load_dwordx2 v[116:117], v[94:95], off offset:3584
	global_load_dwordx4 v[78:81], v[88:89], off offset:16
	global_load_dwordx4 v[82:85], v[96:97], off offset:16
	s_nop 0
	global_load_dwordx4 v[86:89], v[90:91], off offset:48
	global_load_dwordx2 v[118:119], v[92:93], off
	global_load_dwordx2 v[120:121], v[92:93], off offset:512
	global_load_dwordx2 v[122:123], v[92:93], off offset:1024
	global_load_dwordx2 v[124:125], v[92:93], off offset:1536
	global_load_dwordx2 v[126:127], v[92:93], off offset:2048
	global_load_dwordx2 v[128:129], v[92:93], off offset:2560
	global_load_dwordx2 v[130:131], v[92:93], off offset:3072
	global_load_dwordx2 v[132:133], v[92:93], off offset:3584
	global_load_dwordx4 v[36:39], v[98:99], off
	s_nop 0
	global_load_dwordx4 v[90:93], v[98:99], off offset:64
	global_load_dwordx4 v[94:97], v[98:99], off offset:128
	s_nop 0
	global_load_dwordx4 v[98:101], v[98:99], off offset:192
	v_add_u32_e32 v17, v17, v16
	v_cmp_lt_i32_e64 s[0:1], s17, v17
	s_or_b64 s[6:7], s[0:1], s[6:7]
	v_lshl_add_u64 v[22:23], v[22:23], 0, v[24:25]
	v_lshl_add_u64 v[28:29], v[28:29], 0, v[26:27]
	s_waitcnt vmcnt(30)
	v_pk_add_f32 v[44:45], v[44:45], v[48:49]
	v_pk_add_f32 v[42:43], v[42:43], v[46:47]
	s_waitcnt vmcnt(28)
	v_pk_add_f32 v[46:47], v[52:53], v[56:57]
	v_pk_add_f32 v[48:49], v[50:51], v[54:55]
	s_waitcnt vmcnt(27)
	v_lshlrev_b32_e32 v50, 16, v102
	v_and_b32_e32 v51, 0xffff0000, v102
	s_waitcnt vmcnt(12)
	v_pk_add_f32 v[68:69], v[68:69], v[88:89]
	v_pk_add_f32 v[66:67], v[66:67], v[86:87]
	v_pk_add_f32 v[60:61], v[60:61], v[64:65]
	v_pk_add_f32 v[58:59], v[58:59], v[62:63]
	s_waitcnt vmcnt(3)
	v_pk_add_f32 v[38:39], v[38:39], v[72:73]
	v_pk_add_f32 v[36:37], v[36:37], v[70:71]
	s_waitcnt vmcnt(2)
	v_pk_add_f32 v[70:71], v[92:93], v[76:77]
	v_pk_add_f32 v[72:73], v[90:91], v[74:75]
	s_waitcnt vmcnt(1)
	v_pk_add_f32 v[74:75], v[96:97], v[80:81]
	v_pk_add_f32 v[76:77], v[94:95], v[78:79]
	s_waitcnt vmcnt(0)
	v_pk_add_f32 v[78:79], v[100:101], v[84:85]
	v_pk_add_f32 v[80:81], v[98:99], v[82:83]
	v_pk_add_f32 v[38:39], v[38:39], v[68:69]
	v_pk_add_f32 v[36:37], v[36:37], v[66:67]
	v_pk_add_f32 v[44:45], v[70:71], v[44:45]
	v_pk_add_f32 v[42:43], v[72:73], v[42:43]
	v_pk_add_f32 v[46:47], v[74:75], v[46:47]
	v_pk_add_f32 v[48:49], v[76:77], v[48:49]
	v_pk_add_f32 v[60:61], v[78:79], v[60:61]
	v_pk_add_f32 v[58:59], v[80:81], v[58:59]
	v_pk_mov_b32 v[66:67], v[36:37], v[38:39] op_sel:[1,0]
	v_mov_b32_e32 v37, v39
	v_pk_mov_b32 v[38:39], v[42:43], v[44:45] op_sel:[1,0]
	v_mov_b32_e32 v43, v45
	v_pk_mov_b32 v[44:45], v[48:49], v[46:47] op_sel:[1,0]
	v_mov_b32_e32 v49, v47
	v_pk_mov_b32 v[46:47], v[58:59], v[60:61] op_sel:[1,0]
	v_mov_b32_e32 v59, v61
	v_pk_add_f32 v[36:37], v[66:67], v[36:37]
	v_pk_add_f32 v[38:39], v[38:39], v[42:43]
	v_pk_add_f32 v[42:43], v[44:45], v[48:49]
	v_pk_add_f32 v[44:45], v[46:47], v[58:59]
	v_mov_b32_e32 v46, v38
	v_mov_b32_e32 v47, v36
	v_mov_b32_e32 v36, v39
	v_mov_b32_e32 v38, v44
	v_mov_b32_e32 v39, v42
	v_mov_b32_e32 v42, v45
	v_pk_add_f32 v[36:37], v[46:47], v[36:37]
	v_pk_add_f32 v[38:39], v[38:39], v[42:43]
	v_pk_fma_f32 v[36:37], v[36:37], s[16:17], v[30:31] op_sel_hi:[1,0,0]
	v_pk_fma_f32 v[38:39], v[38:39], s[16:17], v[30:31] op_sel_hi:[1,0,0]
	v_mul_f32_e32 v42, 0x4b800000, v37
	v_cmp_gt_f32_e64 s[4:5], s19, v37
	v_mul_f32_e32 v43, 0x4b800000, v36
	v_cmp_gt_f32_e32 vcc, s19, v36
	v_mul_f32_e32 v44, 0x4b800000, v39
	v_mul_f32_e32 v45, 0x4b800000, v38
	v_cmp_gt_f32_e64 s[0:1], s19, v38
	v_cmp_gt_f32_e64 s[2:3], s19, v39
	v_cndmask_b32_e64 v37, v37, v42, s[4:5]
	v_cndmask_b32_e32 v36, v36, v43, vcc
	v_cndmask_b32_e64 v39, v39, v44, s[2:3]
	v_cndmask_b32_e64 v38, v38, v45, s[0:1]
	v_rsq_f32_e32 v37, v37
	v_rsq_f32_e32 v42, v36
	v_rsq_f32_e32 v39, v39
	v_rsq_f32_e32 v43, v38
	v_mul_f32_e32 v36, 0x45800000, v37
	v_lshlrev_b32_e32 v86, 16, v118
	v_and_b32_e32 v87, 0xffff0000, v118
	v_lshlrev_b32_e32 v88, 16, v119
	v_and_b32_e32 v89, 0xffff0000, v119
	v_mul_f32_e32 v38, 0x45800000, v42
	v_mul_f32_e32 v44, 0x45800000, v39
	v_mul_f32_e32 v45, 0x45800000, v43
	v_cndmask_b32_e64 v36, v37, v36, s[4:5]
	v_lshlrev_b32_e32 v52, 16, v103
	v_and_b32_e32 v53, 0xffff0000, v103
	v_lshlrev_b32_e32 v54, 16, v104
	v_and_b32_e32 v55, 0xffff0000, v104
	v_lshlrev_b32_e32 v56, 16, v105
	v_and_b32_e32 v57, 0xffff0000, v105
	v_lshlrev_b32_e32 v102, 16, v106
	v_and_b32_e32 v103, 0xffff0000, v106
	v_lshlrev_b32_e32 v104, 16, v107
	v_and_b32_e32 v105, 0xffff0000, v107
	v_lshlrev_b32_e32 v106, 16, v108
	v_and_b32_e32 v107, 0xffff0000, v108
	v_lshlrev_b32_e32 v108, 16, v109
	v_and_b32_e32 v109, 0xffff0000, v109
	v_lshlrev_b32_e32 v62, 16, v110
	v_and_b32_e32 v63, 0xffff0000, v110
	v_lshlrev_b32_e32 v64, 16, v111
	v_and_b32_e32 v65, 0xffff0000, v111
	v_lshlrev_b32_e32 v110, 16, v112
	v_and_b32_e32 v111, 0xffff0000, v112
	v_lshlrev_b32_e32 v112, 16, v113
	v_and_b32_e32 v113, 0xffff0000, v113
	v_lshlrev_b32_e32 v134, 16, v114
	v_and_b32_e32 v135, 0xffff0000, v114
	v_lshlrev_b32_e32 v114, 16, v115
	v_and_b32_e32 v115, 0xffff0000, v115
	v_lshlrev_b32_e32 v136, 16, v116
	v_and_b32_e32 v137, 0xffff0000, v116
	v_lshlrev_b32_e32 v116, 16, v117
	v_and_b32_e32 v117, 0xffff0000, v117
	v_lshlrev_b32_e32 v118, 16, v120
	v_and_b32_e32 v119, 0xffff0000, v120
	v_lshlrev_b32_e32 v120, 16, v121
	v_and_b32_e32 v121, 0xffff0000, v121
	v_lshlrev_b32_e32 v138, 16, v122
	v_and_b32_e32 v139, 0xffff0000, v122
	v_lshlrev_b32_e32 v122, 16, v123
	v_and_b32_e32 v123, 0xffff0000, v123
	v_lshlrev_b32_e32 v140, 16, v124
	v_and_b32_e32 v141, 0xffff0000, v124
	v_lshlrev_b32_e32 v124, 16, v125
	v_and_b32_e32 v125, 0xffff0000, v125
	v_lshlrev_b32_e32 v142, 16, v126
	v_and_b32_e32 v143, 0xffff0000, v126
	v_lshlrev_b32_e32 v126, 16, v127
	v_and_b32_e32 v127, 0xffff0000, v127
	v_lshlrev_b32_e32 v144, 16, v128
	v_and_b32_e32 v145, 0xffff0000, v128
	v_lshlrev_b32_e32 v128, 16, v129
	v_and_b32_e32 v129, 0xffff0000, v129
	v_lshlrev_b32_e32 v146, 16, v130
	v_and_b32_e32 v147, 0xffff0000, v130
	v_lshlrev_b32_e32 v130, 16, v131
	v_and_b32_e32 v131, 0xffff0000, v131
	v_lshlrev_b32_e32 v148, 16, v132
	v_and_b32_e32 v149, 0xffff0000, v132
	v_lshlrev_b32_e32 v132, 16, v133
	v_and_b32_e32 v133, 0xffff0000, v133
	v_cndmask_b32_e32 v38, v42, v38, vcc
	v_cndmask_b32_e64 v42, v39, v44, s[2:3]
	v_cndmask_b32_e64 v44, v43, v45, s[0:1]
	v_pk_mul_f32 v[46:47], v[36:37], v[86:87] op_sel_hi:[0,1]
	v_pk_mul_f32 v[48:49], v[36:37], v[88:89] op_sel_hi:[0,1]
	v_pk_mul_f32 v[58:59], v[36:37], v[118:119] op_sel_hi:[0,1]
	v_pk_mul_f32 v[60:61], v[36:37], v[120:121] op_sel_hi:[0,1]
	v_pk_mul_f32 v[66:67], v[36:37], v[138:139] op_sel_hi:[0,1]
	v_pk_mul_f32 v[68:69], v[36:37], v[122:123] op_sel_hi:[0,1]
	v_pk_mul_f32 v[70:71], v[36:37], v[140:141] op_sel_hi:[0,1]
	v_pk_mul_f32 v[72:73], v[36:37], v[124:125] op_sel_hi:[0,1]
	v_pk_mul_f32 v[74:75], v[38:39], v[142:143] op_sel_hi:[0,1]
	v_pk_mul_f32 v[76:77], v[38:39], v[126:127] op_sel_hi:[0,1]
	v_pk_mul_f32 v[78:79], v[38:39], v[144:145] op_sel_hi:[0,1]
	v_pk_mul_f32 v[80:81], v[38:39], v[128:129] op_sel_hi:[0,1]
	v_pk_mul_f32 v[82:83], v[38:39], v[146:147] op_sel_hi:[0,1]
	v_pk_mul_f32 v[84:85], v[38:39], v[130:131] op_sel_hi:[0,1]
	v_pk_mul_f32 v[86:87], v[38:39], v[148:149] op_sel_hi:[0,1]
	v_pk_mul_f32 v[88:89], v[38:39], v[132:133] op_sel_hi:[0,1]
	v_pk_mul_f32 v[90:91], v[42:43], v[50:51] op_sel_hi:[0,1]
	v_pk_mul_f32 v[92:93], v[42:43], v[52:53] op_sel_hi:[0,1]
	v_pk_mul_f32 v[94:95], v[42:43], v[54:55] op_sel_hi:[0,1]
	v_pk_mul_f32 v[96:97], v[42:43], v[56:57] op_sel_hi:[0,1]
	v_pk_mul_f32 v[98:99], v[42:43], v[102:103] op_sel_hi:[0,1]
	v_pk_mul_f32 v[100:101], v[42:43], v[104:105] op_sel_hi:[0,1]
	v_pk_mul_f32 v[102:103], v[42:43], v[106:107] op_sel_hi:[0,1]
	v_pk_mul_f32 v[104:105], v[42:43], v[108:109] op_sel_hi:[0,1]
	v_pk_mul_f32 v[106:107], v[44:45], v[62:63] op_sel_hi:[0,1]
	v_pk_mul_f32 v[108:109], v[44:45], v[64:65] op_sel_hi:[0,1]
	v_pk_mul_f32 v[110:111], v[44:45], v[110:111] op_sel_hi:[0,1]
	v_pk_mul_f32 v[112:113], v[44:45], v[112:113] op_sel_hi:[0,1]
	v_pk_mul_f32 v[118:119], v[44:45], v[134:135] op_sel_hi:[0,1]
	v_pk_mul_f32 v[114:115], v[44:45], v[114:115] op_sel_hi:[0,1]
	v_pk_mul_f32 v[120:121], v[44:45], v[136:137] op_sel_hi:[0,1]
	v_pk_mul_f32 v[116:117], v[44:45], v[116:117] op_sel_hi:[0,1]
	v_pk_mul_f32 v[38:39], v[2:3], v[48:49]
	v_pk_mul_f32 v[36:37], v[0:1], v[46:47]
	v_pk_mul_f32 v[44:45], v[6:7], v[60:61]
	v_pk_mul_f32 v[42:43], v[4:5], v[58:59]
	v_pk_mul_f32 v[48:49], v[10:11], v[68:69]
	v_pk_mul_f32 v[46:47], v[8:9], v[66:67]
	v_pk_mul_f32 v[52:53], v[14:15], v[72:73]
	v_pk_mul_f32 v[50:51], v[12:13], v[70:71]
	v_pk_mul_f32 v[56:57], v[2:3], v[76:77]
	v_pk_mul_f32 v[54:55], v[0:1], v[74:75]
	v_pk_mul_f32 v[60:61], v[6:7], v[80:81]
	v_pk_mul_f32 v[58:59], v[4:5], v[78:79]
	v_pk_mul_f32 v[64:65], v[10:11], v[84:85]
	v_pk_mul_f32 v[62:63], v[8:9], v[82:83]
	v_pk_mul_f32 v[68:69], v[14:15], v[88:89]
	v_pk_mul_f32 v[66:67], v[12:13], v[86:87]
	v_pk_mul_f32 v[72:73], v[2:3], v[92:93]
	v_pk_mul_f32 v[70:71], v[0:1], v[90:91]
	v_pk_mul_f32 v[76:77], v[6:7], v[96:97]
	v_pk_mul_f32 v[74:75], v[4:5], v[94:95]
	v_pk_mul_f32 v[80:81], v[10:11], v[100:101]
	v_pk_mul_f32 v[78:79], v[8:9], v[98:99]
	v_pk_mul_f32 v[84:85], v[14:15], v[104:105]
	v_pk_mul_f32 v[82:83], v[12:13], v[102:103]
	v_pk_mul_f32 v[88:89], v[2:3], v[108:109]
	v_pk_mul_f32 v[86:87], v[0:1], v[106:107]
	v_pk_mul_f32 v[92:93], v[6:7], v[112:113]
	v_pk_mul_f32 v[90:91], v[4:5], v[110:111]
	v_pk_mul_f32 v[96:97], v[10:11], v[114:115]
	v_pk_mul_f32 v[94:95], v[8:9], v[118:119]
	v_pk_mul_f32 v[100:101], v[14:15], v[116:117]
	v_pk_mul_f32 v[98:99], v[12:13], v[120:121]
	global_store_dwordx4 v[18:19], v[36:39], off nt
	global_store_dwordx4 v[18:19], v[42:45], off offset:1024 nt
	global_store_dwordx4 v[18:19], v[46:49], off offset:2048 nt
	global_store_dwordx4 v[18:19], v[50:53], off offset:3072 nt
	global_store_dwordx4 v[34:35], v[54:57], off offset:-4096 nt
	global_store_dwordx4 v[32:33], v[58:61], off offset:1024 nt
	global_store_dwordx4 v[32:33], v[62:65], off offset:2048 nt
	global_store_dwordx4 v[32:33], v[66:69], off offset:3072 nt
	global_store_dwordx4 v[34:35], v[70:73], off nt
	global_store_dwordx4 v[34:35], v[74:77], off offset:1024 nt
	global_store_dwordx4 v[34:35], v[78:81], off offset:2048 nt
	global_store_dwordx4 v[34:35], v[82:85], off offset:3072 nt
	global_store_dwordx4 v[40:41], v[86:89], off nt
	global_store_dwordx4 v[40:41], v[90:93], off offset:1024 nt
	global_store_dwordx4 v[40:41], v[94:97], off offset:2048 nt
	global_store_dwordx4 v[40:41], v[98:101], off offset:3072 nt
	v_lshl_add_u64 v[18:19], v[18:19], 0, v[20:21]
	s_andn2_b64 exec, exec, s[6:7]
	s_cbranch_execnz .LBB0_706
